# FFN1 int8 GEMM K-loop: last two LDS-DMA issues of each 6-DMA load segment moved into the following MFMA block, vmcnt(8)->vmcnt(6)
# speedup vs baseline: 1.0035x; 1.0007x over previous
.LBB0_1087:
	v_add_u32_e32 v138, s80, v188
	ds_read_b128 v[148:151], v138
	ds_read_b128 v[152:155], v138 offset:1024
	ds_read_b128 v[156:159], v138 offset:2048
	ds_read_b128 v[160:163], v138 offset:3072
	v_add_u32_e32 v138, s81, v188
	ds_read_b128 v[164:167], v138
	ds_read_b128 v[168:171], v138 offset:1024
	ds_read_b128 v[172:175], v138 offset:2048
	ds_read_b128 v[176:179], v138 offset:3072
	s_add_i32 s84, s34, 2
	s_add_u32 s85, s30, 0x80
	s_addc_u32 s35, s31, 0
	s_cmp_eq_u32 s64, s34
	s_cselect_b32 s34, s2, s85
	s_cselect_b32 s35, s3, s35
	s_cselect_b32 s87, s29, s39
	s_cselect_b32 s86, s28, s38
	v_lshl_add_u64 v[184:185], s[30:31], 0, v[140:141]
	s_add_i32 m0, s50, 0xc000
	ds_read_b128 v[180:183], v189
	ds_read_b128 v[190:193], v189 offset:1024
	ds_read_b128 v[194:197], v189 offset:2048
	ds_read_b128 v[198:201], v189 offset:3072
	ds_read_b128 v[202:205], v189 offset:4096
	ds_read_b128 v[206:209], v189 offset:5120
	ds_read_b128 v[210:213], v189 offset:6144
	ds_read_b128 v[214:217], v189 offset:7168
	global_load_lds_dwordx4 v[184:185], off
	v_lshl_add_u64 v[184:185], s[30:31], 0, v[142:143]
	s_add_i32 m0, s50, 0xe000
	s_nop 0
	global_load_lds_dwordx4 v[184:185], off
	s_waitcnt vmcnt(8)
	s_waitcnt lgkmcnt(0)
	s_barrier
	s_setprio 1
	s_waitcnt lgkmcnt(0)
	v_mfma_i32_16x16x64_i8 v[126:129], v[148:151], v[180:183], v[126:129]
	v_mfma_i32_16x16x64_i8 v[122:125], v[156:159], v[180:183], v[122:125]
	v_mfma_i32_16x16x64_i8 v[118:121], v[148:151], v[194:197], v[118:121]
	v_mfma_i32_16x16x64_i8 v[114:117], v[156:159], v[194:197], v[114:117]
	v_mfma_i32_16x16x64_i8 v[106:109], v[148:151], v[202:205], v[106:109]
	v_mfma_i32_16x16x64_i8 v[98:101], v[156:159], v[202:205], v[98:101]
	v_mfma_i32_16x16x64_i8 v[90:93], v[148:151], v[210:213], v[90:93]
	v_mfma_i32_16x16x64_i8 v[82:85], v[156:159], v[210:213], v[82:85]
	v_mfma_i32_16x16x64_i8 v[126:129], v[152:155], v[190:193], v[126:129]
	v_mfma_i32_16x16x64_i8 v[122:125], v[160:163], v[190:193], v[122:125]
	v_mfma_i32_16x16x64_i8 v[118:121], v[152:155], v[198:201], v[118:121]
	v_mfma_i32_16x16x64_i8 v[114:117], v[160:163], v[198:201], v[114:117]
	v_mfma_i32_16x16x64_i8 v[106:109], v[152:155], v[206:209], v[106:109]
	v_mfma_i32_16x16x64_i8 v[98:101], v[160:163], v[206:209], v[98:101]
	v_mfma_i32_16x16x64_i8 v[90:93], v[152:155], v[214:217], v[90:93]
	v_mfma_i32_16x16x64_i8 v[82:85], v[160:163], v[214:217], v[82:85]
	s_setprio 0
	s_setprio 1
	v_mfma_i32_16x16x64_i8 v[110:113], v[164:167], v[180:183], v[110:113]
	v_mfma_i32_16x16x64_i8 v[102:105], v[172:175], v[180:183], v[102:105]
	v_mfma_i32_16x16x64_i8 v[94:97], v[164:167], v[194:197], v[94:97]
	v_mfma_i32_16x16x64_i8 v[86:89], v[172:175], v[194:197], v[86:89]
	v_mfma_i32_16x16x64_i8 v[78:81], v[164:167], v[202:205], v[78:81]
	v_mfma_i32_16x16x64_i8 v[74:77], v[172:175], v[202:205], v[74:77]
	v_mfma_i32_16x16x64_i8 v[70:73], v[164:167], v[210:213], v[70:73]
	v_mfma_i32_16x16x64_i8 v[66:69], v[172:175], v[210:213], v[66:69]
	v_mfma_i32_16x16x64_i8 v[110:113], v[168:171], v[190:193], v[110:113]
	v_mfma_i32_16x16x64_i8 v[102:105], v[176:179], v[190:193], v[102:105]
	v_mfma_i32_16x16x64_i8 v[94:97], v[168:171], v[198:201], v[94:97]
	v_mfma_i32_16x16x64_i8 v[86:89], v[176:179], v[198:201], v[86:89]
	v_mfma_i32_16x16x64_i8 v[78:81], v[168:171], v[206:209], v[78:81]
	v_mfma_i32_16x16x64_i8 v[74:77], v[176:179], v[206:209], v[74:77]
	v_mfma_i32_16x16x64_i8 v[70:73], v[168:171], v[214:217], v[70:73]
	v_mfma_i32_16x16x64_i8 v[66:69], v[176:179], v[214:217], v[66:69]
	s_setprio 0
	s_barrier
	s_add_i32 s85, s80, s47
	v_lshl_add_u64 v[184:185], s[86:87], 0, v[132:133]
	s_mov_b32 m0, s85
	ds_read_b128 v[180:183], v189 offset:16384
	ds_read_b128 v[190:193], v189 offset:17408
	ds_read_b128 v[194:197], v189 offset:18432
	ds_read_b128 v[198:201], v189 offset:19456
	ds_read_b128 v[202:205], v189 offset:20480
	ds_read_b128 v[206:209], v189 offset:21504
	ds_read_b128 v[210:213], v189 offset:22528
	ds_read_b128 v[214:217], v189 offset:23552
	global_load_lds_dwordx4 v[184:185], off
	s_add_i32 m0, s85, 0x2000
	v_lshl_add_u64 v[218:219], s[86:87], 0, v[136:137]
	s_add_u32 s86, s86, s6
	s_addc_u32 s87, s87, s7
	s_add_i32 s85, s81, s47
	global_load_lds_dwordx4 v[218:219], off
	v_lshl_add_u64 v[220:221], s[86:87], 0, v[132:133]
	s_mov_b32 m0, s85
	v_lshl_add_u64 v[222:223], s[86:87], 0, v[136:137]
	global_load_lds_dwordx4 v[220:221], off
	s_add_i32 m0, s85, 0x2000
	v_lshl_add_u64 v[224:225], s[34:35], 0, v[130:131]
	global_load_lds_dwordx4 v[222:223], off
	s_waitcnt vmcnt(6)
	s_waitcnt lgkmcnt(0)
	s_barrier
	s_setprio 1
	s_waitcnt lgkmcnt(0)
	v_mfma_i32_16x16x64_i8 v[62:65], v[148:151], v[180:183], v[62:65]
	v_mfma_i32_16x16x64_i8 v[58:61], v[156:159], v[180:183], v[58:61]
	v_mfma_i32_16x16x64_i8 v[54:57], v[148:151], v[194:197], v[54:57]
	v_mfma_i32_16x16x64_i8 v[50:53], v[156:159], v[194:197], v[50:53]
	s_mov_b32 m0, s50
	v_lshl_add_u64 v[226:227], s[34:35], 0, v[134:135]
	global_load_lds_dwordx4 v[224:225], off
	v_mfma_i32_16x16x64_i8 v[42:45], v[148:151], v[202:205], v[42:45]
	v_mfma_i32_16x16x64_i8 v[34:37], v[156:159], v[202:205], v[34:37]
	v_mfma_i32_16x16x64_i8 v[26:29], v[148:151], v[210:213], v[26:29]
	v_mfma_i32_16x16x64_i8 v[18:21], v[156:159], v[210:213], v[18:21]
	v_mfma_i32_16x16x64_i8 v[62:65], v[152:155], v[190:193], v[62:65]
	v_mfma_i32_16x16x64_i8 v[58:61], v[160:163], v[190:193], v[58:61]
	v_mfma_i32_16x16x64_i8 v[54:57], v[152:155], v[198:201], v[54:57]
	v_mfma_i32_16x16x64_i8 v[50:53], v[160:163], v[198:201], v[50:53]
	v_mfma_i32_16x16x64_i8 v[42:45], v[152:155], v[206:209], v[42:45]
	v_mfma_i32_16x16x64_i8 v[34:37], v[160:163], v[206:209], v[34:37]
	v_mfma_i32_16x16x64_i8 v[26:29], v[152:155], v[214:217], v[26:29]
	v_mfma_i32_16x16x64_i8 v[18:21], v[160:163], v[214:217], v[18:21]
	s_setprio 0
	s_setprio 1
	v_mfma_i32_16x16x64_i8 v[46:49], v[164:167], v[180:183], v[46:49]
	v_mfma_i32_16x16x64_i8 v[38:41], v[172:175], v[180:183], v[38:41]
	v_mfma_i32_16x16x64_i8 v[30:33], v[164:167], v[194:197], v[30:33]
	v_mfma_i32_16x16x64_i8 v[22:25], v[172:175], v[194:197], v[22:25]
	s_mov_b32 m0, s51
	s_nop 0
	global_load_lds_dwordx4 v[226:227], off
	v_mfma_i32_16x16x64_i8 v[14:17], v[164:167], v[202:205], v[14:17]
	v_mfma_i32_16x16x64_i8 v[10:13], v[172:175], v[202:205], v[10:13]
	v_mfma_i32_16x16x64_i8 v[6:9], v[164:167], v[210:213], v[6:9]
	v_mfma_i32_16x16x64_i8 v[2:5], v[172:175], v[210:213], v[2:5]
	v_mfma_i32_16x16x64_i8 v[46:49], v[168:171], v[190:193], v[46:49]
	v_mfma_i32_16x16x64_i8 v[38:41], v[176:179], v[190:193], v[38:41]
	v_mfma_i32_16x16x64_i8 v[30:33], v[168:171], v[198:201], v[30:33]
	v_mfma_i32_16x16x64_i8 v[22:25], v[176:179], v[198:201], v[22:25]
	v_mfma_i32_16x16x64_i8 v[14:17], v[168:171], v[206:209], v[14:17]
	v_mfma_i32_16x16x64_i8 v[10:13], v[176:179], v[206:209], v[10:13]
	v_mfma_i32_16x16x64_i8 v[6:9], v[168:171], v[214:217], v[6:9]
	v_mfma_i32_16x16x64_i8 v[2:5], v[176:179], v[214:217], v[2:5]
	s_setprio 0
	s_barrier
	s_add_i32 s85, 0, 0x18000
	v_add_u32_e32 v138, s85, v188
	s_add_i32 s86, 0, 0x1c000
	ds_read_b128 v[148:151], v138
	ds_read_b128 v[152:155], v138 offset:1024
	ds_read_b128 v[156:159], v138 offset:2048
	ds_read_b128 v[160:163], v138 offset:3072
	v_add_u32_e32 v138, s86, v188
	ds_read_b128 v[164:167], v138
	ds_read_b128 v[168:171], v138 offset:1024
	ds_read_b128 v[172:175], v138 offset:2048
	ds_read_b128 v[176:179], v138 offset:3072
	s_add_u32 s34, s34, s6
	s_addc_u32 s35, s35, s7
	s_mov_b32 m0, s54
	v_lshl_add_u64 v[228:229], s[34:35], 0, v[130:131]
	ds_read_b128 v[180:183], v189 offset:32768
	ds_read_b128 v[190:193], v189 offset:33792
	ds_read_b128 v[194:197], v189 offset:34816
	ds_read_b128 v[198:201], v189 offset:35840
	ds_read_b128 v[202:205], v189 offset:36864
	ds_read_b128 v[206:209], v189 offset:37888
	ds_read_b128 v[210:213], v189 offset:38912
	ds_read_b128 v[214:217], v189 offset:39936
	global_load_lds_dwordx4 v[228:229], off
	v_lshl_add_u64 v[228:229], s[34:35], 0, v[134:135]
	s_mov_b32 m0, s55
	s_nop 0
	global_load_lds_dwordx4 v[228:229], off
	s_waitcnt vmcnt(8)
	s_waitcnt lgkmcnt(0)
	s_barrier
	s_setprio 1
	s_waitcnt lgkmcnt(0)
	v_mfma_i32_16x16x64_i8 v[126:129], v[148:151], v[180:183], v[126:129]
	v_mfma_i32_16x16x64_i8 v[122:125], v[156:159], v[180:183], v[122:125]
	v_mfma_i32_16x16x64_i8 v[118:121], v[148:151], v[194:197], v[118:121]
	v_mfma_i32_16x16x64_i8 v[114:117], v[156:159], v[194:197], v[114:117]
	v_mfma_i32_16x16x64_i8 v[106:109], v[148:151], v[202:205], v[106:109]
	v_mfma_i32_16x16x64_i8 v[98:101], v[156:159], v[202:205], v[98:101]
	v_mfma_i32_16x16x64_i8 v[90:93], v[148:151], v[210:213], v[90:93]
	v_mfma_i32_16x16x64_i8 v[82:85], v[156:159], v[210:213], v[82:85]
	v_mfma_i32_16x16x64_i8 v[126:129], v[152:155], v[190:193], v[126:129]
	v_mfma_i32_16x16x64_i8 v[122:125], v[160:163], v[190:193], v[122:125]
	v_mfma_i32_16x16x64_i8 v[118:121], v[152:155], v[198:201], v[118:121]
	v_mfma_i32_16x16x64_i8 v[114:117], v[160:163], v[198:201], v[114:117]
	v_mfma_i32_16x16x64_i8 v[106:109], v[152:155], v[206:209], v[106:109]
	v_mfma_i32_16x16x64_i8 v[98:101], v[160:163], v[206:209], v[98:101]
	v_mfma_i32_16x16x64_i8 v[90:93], v[152:155], v[214:217], v[90:93]
	v_mfma_i32_16x16x64_i8 v[82:85], v[160:163], v[214:217], v[82:85]
	s_setprio 0
	s_setprio 1
	v_mfma_i32_16x16x64_i8 v[110:113], v[164:167], v[180:183], v[110:113]
	v_mfma_i32_16x16x64_i8 v[102:105], v[172:175], v[180:183], v[102:105]
	v_mfma_i32_16x16x64_i8 v[94:97], v[164:167], v[194:197], v[94:97]
	v_mfma_i32_16x16x64_i8 v[86:89], v[172:175], v[194:197], v[86:89]
	v_mfma_i32_16x16x64_i8 v[78:81], v[164:167], v[202:205], v[78:81]
	v_mfma_i32_16x16x64_i8 v[74:77], v[172:175], v[202:205], v[74:77]
	v_mfma_i32_16x16x64_i8 v[70:73], v[164:167], v[210:213], v[70:73]
	v_mfma_i32_16x16x64_i8 v[66:69], v[172:175], v[210:213], v[66:69]
	v_mfma_i32_16x16x64_i8 v[110:113], v[168:171], v[190:193], v[110:113]
	v_mfma_i32_16x16x64_i8 v[102:105], v[176:179], v[190:193], v[102:105]
	v_mfma_i32_16x16x64_i8 v[94:97], v[168:171], v[198:201], v[94:97]
	v_mfma_i32_16x16x64_i8 v[86:89], v[176:179], v[198:201], v[86:89]
	v_mfma_i32_16x16x64_i8 v[78:81], v[168:171], v[206:209], v[78:81]
	v_mfma_i32_16x16x64_i8 v[74:77], v[176:179], v[206:209], v[74:77]
	v_mfma_i32_16x16x64_i8 v[70:73], v[168:171], v[214:217], v[70:73]
	v_mfma_i32_16x16x64_i8 v[66:69], v[176:179], v[214:217], v[66:69]
	s_setprio 0
	s_barrier
	s_add_i32 s34, s85, s47
	v_lshl_add_u64 v[184:185], v[184:185], 0, s[22:23]
	s_mov_b32 m0, s34
	ds_read_b128 v[180:183], v189 offset:49152
	ds_read_b128 v[190:193], v189 offset:50176
	ds_read_b128 v[194:197], v189 offset:51200
	ds_read_b128 v[198:201], v189 offset:52224
	ds_read_b128 v[202:205], v189 offset:53248
	ds_read_b128 v[206:209], v189 offset:54272
	ds_read_b128 v[210:213], v189 offset:55296
	ds_read_b128 v[214:217], v189 offset:56320
	global_load_lds_dwordx4 v[184:185], off
	v_lshl_add_u64 v[184:185], v[218:219], 0, s[22:23]
	s_add_i32 m0, s34, 0x2000
	s_add_i32 s34, s86, s47
	global_load_lds_dwordx4 v[184:185], off
	v_lshl_add_u64 v[184:185], v[220:221], 0, s[22:23]
	s_mov_b32 m0, s34
	s_nop 0
	global_load_lds_dwordx4 v[184:185], off
	v_lshl_add_u64 v[184:185], v[222:223], 0, s[22:23]
	s_add_i32 m0, s34, 0x2000
	s_nop 0
	global_load_lds_dwordx4 v[184:185], off
	s_waitcnt vmcnt(6)
	s_waitcnt lgkmcnt(0)
	s_barrier
	s_setprio 1
	s_waitcnt lgkmcnt(0)
	v_mfma_i32_16x16x64_i8 v[62:65], v[148:151], v[180:183], v[62:65]
	v_mfma_i32_16x16x64_i8 v[58:61], v[156:159], v[180:183], v[58:61]
	v_mfma_i32_16x16x64_i8 v[54:57], v[148:151], v[194:197], v[54:57]
	v_mfma_i32_16x16x64_i8 v[50:53], v[156:159], v[194:197], v[50:53]
	v_lshl_add_u64 v[184:185], v[224:225], 0, s[22:23]
	s_mov_b32 m0, s59
	s_nop 0
	global_load_lds_dwordx4 v[184:185], off
	v_mfma_i32_16x16x64_i8 v[42:45], v[148:151], v[202:205], v[42:45]
	v_mfma_i32_16x16x64_i8 v[34:37], v[156:159], v[202:205], v[34:37]
	v_mfma_i32_16x16x64_i8 v[26:29], v[148:151], v[210:213], v[26:29]
	v_mfma_i32_16x16x64_i8 v[18:21], v[156:159], v[210:213], v[18:21]
	v_mfma_i32_16x16x64_i8 v[62:65], v[152:155], v[190:193], v[62:65]
	v_mfma_i32_16x16x64_i8 v[58:61], v[160:163], v[190:193], v[58:61]
	v_mfma_i32_16x16x64_i8 v[54:57], v[152:155], v[198:201], v[54:57]
	v_mfma_i32_16x16x64_i8 v[50:53], v[160:163], v[198:201], v[50:53]
	v_mfma_i32_16x16x64_i8 v[42:45], v[152:155], v[206:209], v[42:45]
	v_mfma_i32_16x16x64_i8 v[34:37], v[160:163], v[206:209], v[34:37]
	v_mfma_i32_16x16x64_i8 v[26:29], v[152:155], v[214:217], v[26:29]
	v_mfma_i32_16x16x64_i8 v[18:21], v[160:163], v[214:217], v[18:21]
	s_setprio 0
	s_setprio 1
	v_mfma_i32_16x16x64_i8 v[46:49], v[164:167], v[180:183], v[46:49]
	v_mfma_i32_16x16x64_i8 v[38:41], v[172:175], v[180:183], v[38:41]
	v_mfma_i32_16x16x64_i8 v[30:33], v[164:167], v[194:197], v[30:33]
	v_mfma_i32_16x16x64_i8 v[22:25], v[172:175], v[194:197], v[22:25]
	v_lshl_add_u64 v[184:185], v[226:227], 0, s[22:23]
	s_mov_b32 m0, s60
	s_nop 0
	global_load_lds_dwordx4 v[184:185], off
	v_mfma_i32_16x16x64_i8 v[14:17], v[164:167], v[202:205], v[14:17]
	v_mfma_i32_16x16x64_i8 v[10:13], v[172:175], v[202:205], v[10:13]
	v_mfma_i32_16x16x64_i8 v[6:9], v[164:167], v[210:213], v[6:9]
	v_mfma_i32_16x16x64_i8 v[2:5], v[172:175], v[210:213], v[2:5]
	v_mfma_i32_16x16x64_i8 v[46:49], v[168:171], v[190:193], v[46:49]
	v_mfma_i32_16x16x64_i8 v[38:41], v[176:179], v[190:193], v[38:41]
	v_mfma_i32_16x16x64_i8 v[30:33], v[168:171], v[198:201], v[30:33]
	v_mfma_i32_16x16x64_i8 v[22:25], v[176:179], v[198:201], v[22:25]
	v_mfma_i32_16x16x64_i8 v[14:17], v[168:171], v[206:209], v[14:17]
	v_mfma_i32_16x16x64_i8 v[10:13], v[176:179], v[206:209], v[10:13]
	v_mfma_i32_16x16x64_i8 v[6:9], v[168:171], v[214:217], v[6:9]
	v_mfma_i32_16x16x64_i8 v[2:5], v[176:179], v[214:217], v[2:5]
	s_setprio 0
	s_barrier
	s_add_u32 s30, s30, 0x100
	s_addc_u32 s31, s31, 0
	s_add_u32 s38, s38, 0x100
	s_addc_u32 s39, s39, 0
	s_cmp_ge_i32 s84, s61
	s_mov_b32 s34, s84
	s_cbranch_scc0 .LBB0_1087
	v_cvt_f32_i32_e32 v172, v126
	v_cvt_f32_i32_e32 v173, v127
	v_cvt_f32_i32_e32 v170, v128
	v_cvt_f32_i32_e32 v171, v129
	v_cvt_f32_i32_e32 v174, v122
	v_cvt_f32_i32_e32 v175, v123
	v_cvt_f32_i32_e32 v176, v124
	v_cvt_f32_i32_e32 v177, v125
	v_cvt_f32_i32_e32 v180, v110
	v_cvt_f32_i32_e32 v181, v111
	v_cvt_f32_i32_e32 v182, v112
	v_cvt_f32_i32_e32 v183, v113
	v_cvt_f32_i32_e32 v178, v102
	v_cvt_f32_i32_e32 v179, v103
	v_cvt_f32_i32_e32 v184, v104
	v_cvt_f32_i32_e32 v185, v105
	v_cvt_f32_i32_e32 v152, v118
	v_cvt_f32_i32_e32 v153, v119
	v_cvt_f32_i32_e32 v154, v120
	v_cvt_f32_i32_e32 v155, v121
	v_cvt_f32_i32_e32 v156, v114
	v_cvt_f32_i32_e32 v157, v115
	v_cvt_f32_i32_e32 v158, v116
	v_cvt_f32_i32_e32 v159, v117
	v_cvt_f32_i32_e32 v160, v94
	v_cvt_f32_i32_e32 v161, v95
	v_cvt_f32_i32_e32 v162, v96
	v_cvt_f32_i32_e32 v163, v97
	v_cvt_f32_i32_e32 v164, v86
	v_cvt_f32_i32_e32 v165, v87
	v_cvt_f32_i32_e32 v166, v88
	v_cvt_f32_i32_e32 v167, v89
	v_cvt_f32_i32_e32 v118, v106
	v_cvt_f32_i32_e32 v119, v107
	v_cvt_f32_i32_e32 v120, v108
	v_cvt_f32_i32_e32 v121, v109
	v_cvt_f32_i32_e32 v122, v98
	v_cvt_f32_i32_e32 v123, v99
	v_cvt_f32_i32_e32 v124, v100
	v_cvt_f32_i32_e32 v125, v101
	v_cvt_f32_i32_e32 v126, v78
	v_cvt_f32_i32_e32 v127, v79
	v_cvt_f32_i32_e32 v128, v80
	v_cvt_f32_i32_e32 v129, v81
	v_cvt_f32_i32_e32 v148, v74
	v_cvt_f32_i32_e32 v149, v75
	v_cvt_f32_i32_e32 v150, v76
	v_cvt_f32_i32_e32 v151, v77
	v_cvt_f32_i32_e32 v102, v90
	v_cvt_f32_i32_e32 v103, v91
	v_cvt_f32_i32_e32 v104, v92
	v_cvt_f32_i32_e32 v105, v93
	v_cvt_f32_i32_e32 v106, v82
	v_cvt_f32_i32_e32 v107, v83
	v_cvt_f32_i32_e32 v108, v84
	v_cvt_f32_i32_e32 v109, v85
	v_cvt_f32_i32_e32 v110, v70
	v_cvt_f32_i32_e32 v111, v71
	v_cvt_f32_i32_e32 v112, v72
	v_cvt_f32_i32_e32 v113, v73
	v_cvt_f32_i32_e32 v114, v66
	v_cvt_f32_i32_e32 v115, v67
	v_cvt_f32_i32_e32 v116, v68
	v_cvt_f32_i32_e32 v117, v69
	v_cvt_f32_i32_e32 v82, v62
	v_cvt_f32_i32_e32 v83, v63
	v_cvt_f32_i32_e32 v84, v64
	v_cvt_f32_i32_e32 v85, v65
	v_cvt_f32_i32_e32 v86, v58
	v_cvt_f32_i32_e32 v87, v59
	v_cvt_f32_i32_e32 v88, v60
	v_cvt_f32_i32_e32 v89, v61
	v_cvt_f32_i32_e32 v92, v46
	v_cvt_f32_i32_e32 v93, v47
	v_cvt_f32_i32_e32 v94, v48
	v_cvt_f32_i32_e32 v95, v49
	v_cvt_f32_i32_e32 v96, v38
	v_cvt_f32_i32_e32 v97, v39
	v_cvt_f32_i32_e32 v98, v40
	v_cvt_f32_i32_e32 v99, v41
	v_cvt_f32_i32_e32 v66, v54
	v_cvt_f32_i32_e32 v67, v55
	v_cvt_f32_i32_e32 v68, v56
	v_cvt_f32_i32_e32 v69, v57
	v_cvt_f32_i32_e32 v70, v50
	v_cvt_f32_i32_e32 v71, v51
	v_cvt_f32_i32_e32 v72, v52
	v_cvt_f32_i32_e32 v73, v53
	v_cvt_f32_i32_e32 v74, v30
	v_cvt_f32_i32_e32 v75, v31
	v_cvt_f32_i32_e32 v76, v32
	v_cvt_f32_i32_e32 v77, v33
	v_cvt_f32_i32_e32 v78, v22
	v_cvt_f32_i32_e32 v79, v23
	v_cvt_f32_i32_e32 v80, v24
	v_cvt_f32_i32_e32 v81, v25
	v_cvt_f32_i32_e32 v50, v42
	v_cvt_f32_i32_e32 v51, v43
	v_cvt_f32_i32_e32 v52, v44
	v_cvt_f32_i32_e32 v53, v45
	v_cvt_f32_i32_e32 v54, v34
	v_cvt_f32_i32_e32 v55, v35
	v_cvt_f32_i32_e32 v56, v36
	v_cvt_f32_i32_e32 v57, v37
	v_cvt_f32_i32_e32 v58, v14
	v_cvt_f32_i32_e32 v59, v15
	v_cvt_f32_i32_e32 v60, v16
	v_cvt_f32_i32_e32 v61, v17
	v_cvt_f32_i32_e32 v62, v10
	v_cvt_f32_i32_e32 v63, v11
	v_cvt_f32_i32_e32 v64, v12
	v_cvt_f32_i32_e32 v65, v13
	v_cvt_f32_i32_e32 v34, v26
	v_cvt_f32_i32_e32 v35, v27
	v_cvt_f32_i32_e32 v36, v28
	v_cvt_f32_i32_e32 v37, v29
	v_cvt_f32_i32_e32 v38, v18
	v_cvt_f32_i32_e32 v39, v19
	v_cvt_f32_i32_e32 v40, v20
	v_cvt_f32_i32_e32 v41, v21
	v_cvt_f32_i32_e32 v42, v6
	v_cvt_f32_i32_e32 v43, v7
	v_cvt_f32_i32_e32 v44, v8
	v_cvt_f32_i32_e32 v45, v9
	v_cvt_f32_i32_e32 v46, v2
	v_cvt_f32_i32_e32 v47, v3
	v_cvt_f32_i32_e32 v48, v4
	v_cvt_f32_i32_e32 v49, v5

.LBB0_1939:
	v_add_u32_e32 v138, s62, v188
	ds_read_b128 v[148:151], v138
	ds_read_b128 v[152:155], v138 offset:1024
	ds_read_b128 v[156:159], v138 offset:2048
	ds_read_b128 v[160:163], v138 offset:3072
	v_add_u32_e32 v138, s63, v188
	ds_read_b128 v[164:167], v138
	ds_read_b128 v[168:171], v138 offset:1024
	ds_read_b128 v[172:175], v138 offset:2048
	ds_read_b128 v[176:179], v138 offset:3072
	s_add_i32 s66, s28, 2
	s_add_u32 s67, s26, 0x80
	s_addc_u32 s29, s27, 0
	s_cmp_eq_u32 s60, s28
	s_cselect_b32 s28, s2, s67
	s_cselect_b32 s29, s3, s29
	s_cselect_b32 s69, s25, s35
	s_cselect_b32 s68, s24, s34
	v_lshl_add_u64 v[184:185], s[26:27], 0, v[140:141]
	s_add_i32 m0, s44, 0xc000
	ds_read_b128 v[180:183], v189
	ds_read_b128 v[190:193], v189 offset:1024
	ds_read_b128 v[194:197], v189 offset:2048
	ds_read_b128 v[198:201], v189 offset:3072
	ds_read_b128 v[202:205], v189 offset:4096
	ds_read_b128 v[206:209], v189 offset:5120
	ds_read_b128 v[210:213], v189 offset:6144
	ds_read_b128 v[214:217], v189 offset:7168
	global_load_lds_dwordx4 v[184:185], off
	v_lshl_add_u64 v[184:185], s[26:27], 0, v[142:143]
	s_add_i32 m0, s44, 0xe000
	s_nop 0
	global_load_lds_dwordx4 v[184:185], off
	s_waitcnt vmcnt(8)
	s_waitcnt lgkmcnt(0)
	s_barrier
	s_setprio 1
	s_waitcnt lgkmcnt(0)
	v_mfma_i32_16x16x64_i8 v[126:129], v[148:151], v[180:183], v[126:129]
	v_mfma_i32_16x16x64_i8 v[122:125], v[156:159], v[180:183], v[122:125]
	v_mfma_i32_16x16x64_i8 v[118:121], v[148:151], v[194:197], v[118:121]
	v_mfma_i32_16x16x64_i8 v[114:117], v[156:159], v[194:197], v[114:117]
	v_mfma_i32_16x16x64_i8 v[106:109], v[148:151], v[202:205], v[106:109]
	v_mfma_i32_16x16x64_i8 v[98:101], v[156:159], v[202:205], v[98:101]
	v_mfma_i32_16x16x64_i8 v[90:93], v[148:151], v[210:213], v[90:93]
	v_mfma_i32_16x16x64_i8 v[82:85], v[156:159], v[210:213], v[82:85]
	v_mfma_i32_16x16x64_i8 v[126:129], v[152:155], v[190:193], v[126:129]
	v_mfma_i32_16x16x64_i8 v[122:125], v[160:163], v[190:193], v[122:125]
	v_mfma_i32_16x16x64_i8 v[118:121], v[152:155], v[198:201], v[118:121]
	v_mfma_i32_16x16x64_i8 v[114:117], v[160:163], v[198:201], v[114:117]
	v_mfma_i32_16x16x64_i8 v[106:109], v[152:155], v[206:209], v[106:109]
	v_mfma_i32_16x16x64_i8 v[98:101], v[160:163], v[206:209], v[98:101]
	v_mfma_i32_16x16x64_i8 v[90:93], v[152:155], v[214:217], v[90:93]
	v_mfma_i32_16x16x64_i8 v[82:85], v[160:163], v[214:217], v[82:85]
	s_setprio 0
	s_setprio 1
	v_mfma_i32_16x16x64_i8 v[110:113], v[164:167], v[180:183], v[110:113]
	v_mfma_i32_16x16x64_i8 v[102:105], v[172:175], v[180:183], v[102:105]
	v_mfma_i32_16x16x64_i8 v[94:97], v[164:167], v[194:197], v[94:97]
	v_mfma_i32_16x16x64_i8 v[86:89], v[172:175], v[194:197], v[86:89]
	v_mfma_i32_16x16x64_i8 v[78:81], v[164:167], v[202:205], v[78:81]
	v_mfma_i32_16x16x64_i8 v[74:77], v[172:175], v[202:205], v[74:77]
	v_mfma_i32_16x16x64_i8 v[70:73], v[164:167], v[210:213], v[70:73]
	v_mfma_i32_16x16x64_i8 v[66:69], v[172:175], v[210:213], v[66:69]
	v_mfma_i32_16x16x64_i8 v[110:113], v[168:171], v[190:193], v[110:113]
	v_mfma_i32_16x16x64_i8 v[102:105], v[176:179], v[190:193], v[102:105]
	v_mfma_i32_16x16x64_i8 v[94:97], v[168:171], v[198:201], v[94:97]
	v_mfma_i32_16x16x64_i8 v[86:89], v[176:179], v[198:201], v[86:89]
	v_mfma_i32_16x16x64_i8 v[78:81], v[168:171], v[206:209], v[78:81]
	v_mfma_i32_16x16x64_i8 v[74:77], v[176:179], v[206:209], v[74:77]
	v_mfma_i32_16x16x64_i8 v[70:73], v[168:171], v[214:217], v[70:73]
	v_mfma_i32_16x16x64_i8 v[66:69], v[176:179], v[214:217], v[66:69]
	s_setprio 0
	s_barrier
	s_add_i32 s67, s62, s43
	v_lshl_add_u64 v[184:185], s[68:69], 0, v[132:133]
	s_mov_b32 m0, s67
	ds_read_b128 v[180:183], v189 offset:16384
	ds_read_b128 v[190:193], v189 offset:17408
	ds_read_b128 v[194:197], v189 offset:18432
	ds_read_b128 v[198:201], v189 offset:19456
	ds_read_b128 v[202:205], v189 offset:20480
	ds_read_b128 v[206:209], v189 offset:21504
	ds_read_b128 v[210:213], v189 offset:22528
	ds_read_b128 v[214:217], v189 offset:23552
	global_load_lds_dwordx4 v[184:185], off
	s_add_i32 m0, s67, 0x2000
	v_lshl_add_u64 v[218:219], s[68:69], 0, v[136:137]
	s_add_u32 s68, s68, s6
	s_addc_u32 s69, s69, s7
	s_add_i32 s67, s63, s43
	global_load_lds_dwordx4 v[218:219], off
	v_lshl_add_u64 v[220:221], s[68:69], 0, v[132:133]
	s_mov_b32 m0, s67
	v_lshl_add_u64 v[222:223], s[68:69], 0, v[136:137]
	global_load_lds_dwordx4 v[220:221], off
	s_add_i32 m0, s67, 0x2000
	v_lshl_add_u64 v[224:225], s[28:29], 0, v[130:131]
	global_load_lds_dwordx4 v[222:223], off
	s_waitcnt vmcnt(6)
	s_waitcnt lgkmcnt(0)
	s_barrier
	s_setprio 1
	s_waitcnt lgkmcnt(0)
	v_mfma_i32_16x16x64_i8 v[62:65], v[148:151], v[180:183], v[62:65]
	v_mfma_i32_16x16x64_i8 v[58:61], v[156:159], v[180:183], v[58:61]
	v_mfma_i32_16x16x64_i8 v[54:57], v[148:151], v[194:197], v[54:57]
	v_mfma_i32_16x16x64_i8 v[50:53], v[156:159], v[194:197], v[50:53]
	s_mov_b32 m0, s44
	v_lshl_add_u64 v[226:227], s[28:29], 0, v[134:135]
	global_load_lds_dwordx4 v[224:225], off
	v_mfma_i32_16x16x64_i8 v[42:45], v[148:151], v[202:205], v[42:45]
	v_mfma_i32_16x16x64_i8 v[34:37], v[156:159], v[202:205], v[34:37]
	v_mfma_i32_16x16x64_i8 v[26:29], v[148:151], v[210:213], v[26:29]
	v_mfma_i32_16x16x64_i8 v[18:21], v[156:159], v[210:213], v[18:21]
	v_mfma_i32_16x16x64_i8 v[62:65], v[152:155], v[190:193], v[62:65]
	v_mfma_i32_16x16x64_i8 v[58:61], v[160:163], v[190:193], v[58:61]
	v_mfma_i32_16x16x64_i8 v[54:57], v[152:155], v[198:201], v[54:57]
	v_mfma_i32_16x16x64_i8 v[50:53], v[160:163], v[198:201], v[50:53]
	v_mfma_i32_16x16x64_i8 v[42:45], v[152:155], v[206:209], v[42:45]
	v_mfma_i32_16x16x64_i8 v[34:37], v[160:163], v[206:209], v[34:37]
	v_mfma_i32_16x16x64_i8 v[26:29], v[152:155], v[214:217], v[26:29]
	v_mfma_i32_16x16x64_i8 v[18:21], v[160:163], v[214:217], v[18:21]
	s_setprio 0
	s_setprio 1
	v_mfma_i32_16x16x64_i8 v[46:49], v[164:167], v[180:183], v[46:49]
	v_mfma_i32_16x16x64_i8 v[38:41], v[172:175], v[180:183], v[38:41]
	v_mfma_i32_16x16x64_i8 v[30:33], v[164:167], v[194:197], v[30:33]
	v_mfma_i32_16x16x64_i8 v[22:25], v[172:175], v[194:197], v[22:25]
	s_mov_b32 m0, s45
	s_nop 0
	global_load_lds_dwordx4 v[226:227], off
	v_mfma_i32_16x16x64_i8 v[14:17], v[164:167], v[202:205], v[14:17]
	v_mfma_i32_16x16x64_i8 v[10:13], v[172:175], v[202:205], v[10:13]
	v_mfma_i32_16x16x64_i8 v[6:9], v[164:167], v[210:213], v[6:9]
	v_mfma_i32_16x16x64_i8 v[2:5], v[172:175], v[210:213], v[2:5]
	v_mfma_i32_16x16x64_i8 v[46:49], v[168:171], v[190:193], v[46:49]
	v_mfma_i32_16x16x64_i8 v[38:41], v[176:179], v[190:193], v[38:41]
	v_mfma_i32_16x16x64_i8 v[30:33], v[168:171], v[198:201], v[30:33]
	v_mfma_i32_16x16x64_i8 v[22:25], v[176:179], v[198:201], v[22:25]
	v_mfma_i32_16x16x64_i8 v[14:17], v[168:171], v[206:209], v[14:17]
	v_mfma_i32_16x16x64_i8 v[10:13], v[176:179], v[206:209], v[10:13]
	v_mfma_i32_16x16x64_i8 v[6:9], v[168:171], v[214:217], v[6:9]
	v_mfma_i32_16x16x64_i8 v[2:5], v[176:179], v[214:217], v[2:5]
	s_setprio 0
	s_barrier
	s_add_i32 s67, 0, 0x18000
	v_add_u32_e32 v138, s67, v188
	s_add_i32 s68, 0, 0x1c000
	ds_read_b128 v[148:151], v138
	ds_read_b128 v[152:155], v138 offset:1024
	ds_read_b128 v[156:159], v138 offset:2048
	ds_read_b128 v[160:163], v138 offset:3072
	v_add_u32_e32 v138, s68, v188
	ds_read_b128 v[164:167], v138
	ds_read_b128 v[168:171], v138 offset:1024
	ds_read_b128 v[172:175], v138 offset:2048
	ds_read_b128 v[176:179], v138 offset:3072
	s_add_u32 s28, s28, s6
	s_addc_u32 s29, s29, s7
	s_mov_b32 m0, s46
	v_lshl_add_u64 v[228:229], s[28:29], 0, v[130:131]
	ds_read_b128 v[180:183], v189 offset:32768
	ds_read_b128 v[190:193], v189 offset:33792
	ds_read_b128 v[194:197], v189 offset:34816
	ds_read_b128 v[198:201], v189 offset:35840
	ds_read_b128 v[202:205], v189 offset:36864
	ds_read_b128 v[206:209], v189 offset:37888
	ds_read_b128 v[210:213], v189 offset:38912
	ds_read_b128 v[214:217], v189 offset:39936
	global_load_lds_dwordx4 v[228:229], off
	v_lshl_add_u64 v[228:229], s[28:29], 0, v[134:135]
	s_mov_b32 m0, s47
	s_nop 0
	global_load_lds_dwordx4 v[228:229], off
	s_waitcnt vmcnt(8)
	s_waitcnt lgkmcnt(0)
	s_barrier
	s_setprio 1
	s_waitcnt lgkmcnt(0)
	v_mfma_i32_16x16x64_i8 v[126:129], v[148:151], v[180:183], v[126:129]
	v_mfma_i32_16x16x64_i8 v[122:125], v[156:159], v[180:183], v[122:125]
	v_mfma_i32_16x16x64_i8 v[118:121], v[148:151], v[194:197], v[118:121]
	v_mfma_i32_16x16x64_i8 v[114:117], v[156:159], v[194:197], v[114:117]
	v_mfma_i32_16x16x64_i8 v[106:109], v[148:151], v[202:205], v[106:109]
	v_mfma_i32_16x16x64_i8 v[98:101], v[156:159], v[202:205], v[98:101]
	v_mfma_i32_16x16x64_i8 v[90:93], v[148:151], v[210:213], v[90:93]
	v_mfma_i32_16x16x64_i8 v[82:85], v[156:159], v[210:213], v[82:85]
	v_mfma_i32_16x16x64_i8 v[126:129], v[152:155], v[190:193], v[126:129]
	v_mfma_i32_16x16x64_i8 v[122:125], v[160:163], v[190:193], v[122:125]
	v_mfma_i32_16x16x64_i8 v[118:121], v[152:155], v[198:201], v[118:121]
	v_mfma_i32_16x16x64_i8 v[114:117], v[160:163], v[198:201], v[114:117]
	v_mfma_i32_16x16x64_i8 v[106:109], v[152:155], v[206:209], v[106:109]
	v_mfma_i32_16x16x64_i8 v[98:101], v[160:163], v[206:209], v[98:101]
	v_mfma_i32_16x16x64_i8 v[90:93], v[152:155], v[214:217], v[90:93]
	v_mfma_i32_16x16x64_i8 v[82:85], v[160:163], v[214:217], v[82:85]
	s_setprio 0
	s_setprio 1
	v_mfma_i32_16x16x64_i8 v[110:113], v[164:167], v[180:183], v[110:113]
	v_mfma_i32_16x16x64_i8 v[102:105], v[172:175], v[180:183], v[102:105]
	v_mfma_i32_16x16x64_i8 v[94:97], v[164:167], v[194:197], v[94:97]
	v_mfma_i32_16x16x64_i8 v[86:89], v[172:175], v[194:197], v[86:89]
	v_mfma_i32_16x16x64_i8 v[78:81], v[164:167], v[202:205], v[78:81]
	v_mfma_i32_16x16x64_i8 v[74:77], v[172:175], v[202:205], v[74:77]
	v_mfma_i32_16x16x64_i8 v[70:73], v[164:167], v[210:213], v[70:73]
	v_mfma_i32_16x16x64_i8 v[66:69], v[172:175], v[210:213], v[66:69]
	v_mfma_i32_16x16x64_i8 v[110:113], v[168:171], v[190:193], v[110:113]
	v_mfma_i32_16x16x64_i8 v[102:105], v[176:179], v[190:193], v[102:105]
	v_mfma_i32_16x16x64_i8 v[94:97], v[168:171], v[198:201], v[94:97]
	v_mfma_i32_16x16x64_i8 v[86:89], v[176:179], v[198:201], v[86:89]
	v_mfma_i32_16x16x64_i8 v[78:81], v[168:171], v[206:209], v[78:81]
	v_mfma_i32_16x16x64_i8 v[74:77], v[176:179], v[206:209], v[74:77]
	v_mfma_i32_16x16x64_i8 v[70:73], v[168:171], v[214:217], v[70:73]
	v_mfma_i32_16x16x64_i8 v[66:69], v[176:179], v[214:217], v[66:69]
	s_setprio 0
	s_barrier
	s_add_i32 s28, s67, s43
	v_lshl_add_u64 v[184:185], v[184:185], 0, s[18:19]
	s_mov_b32 m0, s28
	ds_read_b128 v[180:183], v189 offset:49152
	ds_read_b128 v[190:193], v189 offset:50176
	ds_read_b128 v[194:197], v189 offset:51200
	ds_read_b128 v[198:201], v189 offset:52224
	ds_read_b128 v[202:205], v189 offset:53248
	ds_read_b128 v[206:209], v189 offset:54272
	ds_read_b128 v[210:213], v189 offset:55296
	ds_read_b128 v[214:217], v189 offset:56320
	global_load_lds_dwordx4 v[184:185], off
	v_lshl_add_u64 v[184:185], v[218:219], 0, s[18:19]
	s_add_i32 m0, s28, 0x2000
	s_add_i32 s28, s68, s43
	global_load_lds_dwordx4 v[184:185], off
	v_lshl_add_u64 v[184:185], v[220:221], 0, s[18:19]
	s_mov_b32 m0, s28
	s_nop 0
	global_load_lds_dwordx4 v[184:185], off
	v_lshl_add_u64 v[184:185], v[222:223], 0, s[18:19]
	s_add_i32 m0, s28, 0x2000
	s_nop 0
	global_load_lds_dwordx4 v[184:185], off
	s_waitcnt vmcnt(6)
	s_waitcnt lgkmcnt(0)
	s_barrier
	s_setprio 1
	s_waitcnt lgkmcnt(0)
	v_mfma_i32_16x16x64_i8 v[62:65], v[148:151], v[180:183], v[62:65]
	v_mfma_i32_16x16x64_i8 v[58:61], v[156:159], v[180:183], v[58:61]
	v_mfma_i32_16x16x64_i8 v[54:57], v[148:151], v[194:197], v[54:57]
	v_mfma_i32_16x16x64_i8 v[50:53], v[156:159], v[194:197], v[50:53]
	v_lshl_add_u64 v[184:185], v[224:225], 0, s[18:19]
	s_mov_b32 m0, s55
	s_nop 0
	global_load_lds_dwordx4 v[184:185], off
	v_mfma_i32_16x16x64_i8 v[42:45], v[148:151], v[202:205], v[42:45]
	v_mfma_i32_16x16x64_i8 v[34:37], v[156:159], v[202:205], v[34:37]
	v_mfma_i32_16x16x64_i8 v[26:29], v[148:151], v[210:213], v[26:29]
	v_mfma_i32_16x16x64_i8 v[18:21], v[156:159], v[210:213], v[18:21]
	v_mfma_i32_16x16x64_i8 v[62:65], v[152:155], v[190:193], v[62:65]
	v_mfma_i32_16x16x64_i8 v[58:61], v[160:163], v[190:193], v[58:61]
	v_mfma_i32_16x16x64_i8 v[54:57], v[152:155], v[198:201], v[54:57]
	v_mfma_i32_16x16x64_i8 v[50:53], v[160:163], v[198:201], v[50:53]
	v_mfma_i32_16x16x64_i8 v[42:45], v[152:155], v[206:209], v[42:45]
	v_mfma_i32_16x16x64_i8 v[34:37], v[160:163], v[206:209], v[34:37]
	v_mfma_i32_16x16x64_i8 v[26:29], v[152:155], v[214:217], v[26:29]
	v_mfma_i32_16x16x64_i8 v[18:21], v[160:163], v[214:217], v[18:21]
	s_setprio 0
	s_setprio 1
	v_mfma_i32_16x16x64_i8 v[46:49], v[164:167], v[180:183], v[46:49]
	v_mfma_i32_16x16x64_i8 v[38:41], v[172:175], v[180:183], v[38:41]
	v_mfma_i32_16x16x64_i8 v[30:33], v[164:167], v[194:197], v[30:33]
	v_mfma_i32_16x16x64_i8 v[22:25], v[172:175], v[194:197], v[22:25]
	v_lshl_add_u64 v[184:185], v[226:227], 0, s[18:19]
	s_mov_b32 m0, s56
	s_nop 0
	global_load_lds_dwordx4 v[184:185], off
	v_mfma_i32_16x16x64_i8 v[14:17], v[164:167], v[202:205], v[14:17]
	v_mfma_i32_16x16x64_i8 v[10:13], v[172:175], v[202:205], v[10:13]
	v_mfma_i32_16x16x64_i8 v[6:9], v[164:167], v[210:213], v[6:9]
	v_mfma_i32_16x16x64_i8 v[2:5], v[172:175], v[210:213], v[2:5]
	v_mfma_i32_16x16x64_i8 v[46:49], v[168:171], v[190:193], v[46:49]
	v_mfma_i32_16x16x64_i8 v[38:41], v[176:179], v[190:193], v[38:41]
	v_mfma_i32_16x16x64_i8 v[30:33], v[168:171], v[198:201], v[30:33]
	v_mfma_i32_16x16x64_i8 v[22:25], v[176:179], v[198:201], v[22:25]
	v_mfma_i32_16x16x64_i8 v[14:17], v[168:171], v[206:209], v[14:17]
	v_mfma_i32_16x16x64_i8 v[10:13], v[176:179], v[206:209], v[10:13]
	v_mfma_i32_16x16x64_i8 v[6:9], v[168:171], v[214:217], v[6:9]
	v_mfma_i32_16x16x64_i8 v[2:5], v[176:179], v[214:217], v[2:5]
	s_setprio 0
	s_barrier
	s_add_u32 s26, s26, 0x100
	s_addc_u32 s27, s27, 0
	s_add_u32 s34, s34, 0x100
	s_addc_u32 s35, s35, 0
	s_cmp_ge_i32 s66, s57
	s_mov_b32 s28, s66
	s_cbranch_scc0 .LBB0_1939
	v_cvt_f32_i32_e32 v172, v126
	v_cvt_f32_i32_e32 v173, v127
	v_cvt_f32_i32_e32 v170, v128
	v_cvt_f32_i32_e32 v171, v129
	v_cvt_f32_i32_e32 v174, v122
	v_cvt_f32_i32_e32 v175, v123
	v_cvt_f32_i32_e32 v176, v124
	v_cvt_f32_i32_e32 v177, v125
	v_cvt_f32_i32_e32 v180, v110
	v_cvt_f32_i32_e32 v181, v111
	v_cvt_f32_i32_e32 v182, v112
	v_cvt_f32_i32_e32 v183, v113
	v_cvt_f32_i32_e32 v178, v102
	v_cvt_f32_i32_e32 v179, v103
	v_cvt_f32_i32_e32 v184, v104
	v_cvt_f32_i32_e32 v185, v105
	v_cvt_f32_i32_e32 v152, v118
	v_cvt_f32_i32_e32 v153, v119
	v_cvt_f32_i32_e32 v154, v120
	v_cvt_f32_i32_e32 v155, v121
	v_cvt_f32_i32_e32 v156, v114
	v_cvt_f32_i32_e32 v157, v115
	v_cvt_f32_i32_e32 v158, v116
	v_cvt_f32_i32_e32 v159, v117
	v_cvt_f32_i32_e32 v160, v94
	v_cvt_f32_i32_e32 v161, v95
	v_cvt_f32_i32_e32 v162, v96
	v_cvt_f32_i32_e32 v163, v97
	v_cvt_f32_i32_e32 v164, v86
	v_cvt_f32_i32_e32 v165, v87
	v_cvt_f32_i32_e32 v166, v88
	v_cvt_f32_i32_e32 v167, v89
	v_cvt_f32_i32_e32 v118, v106
	v_cvt_f32_i32_e32 v119, v107
	v_cvt_f32_i32_e32 v120, v108
	v_cvt_f32_i32_e32 v121, v109
	v_cvt_f32_i32_e32 v122, v98
	v_cvt_f32_i32_e32 v123, v99
	v_cvt_f32_i32_e32 v124, v100
	v_cvt_f32_i32_e32 v125, v101
	v_cvt_f32_i32_e32 v126, v78
	v_cvt_f32_i32_e32 v127, v79
	v_cvt_f32_i32_e32 v128, v80
	v_cvt_f32_i32_e32 v129, v81
	v_cvt_f32_i32_e32 v148, v74
	v_cvt_f32_i32_e32 v149, v75
	v_cvt_f32_i32_e32 v150, v76
	v_cvt_f32_i32_e32 v151, v77
	v_cvt_f32_i32_e32 v102, v90
	v_cvt_f32_i32_e32 v103, v91
	v_cvt_f32_i32_e32 v104, v92
	v_cvt_f32_i32_e32 v105, v93
	v_cvt_f32_i32_e32 v106, v82
	v_cvt_f32_i32_e32 v107, v83
	v_cvt_f32_i32_e32 v108, v84
	v_cvt_f32_i32_e32 v109, v85
	v_cvt_f32_i32_e32 v110, v70
	v_cvt_f32_i32_e32 v111, v71
	v_cvt_f32_i32_e32 v112, v72
	v_cvt_f32_i32_e32 v113, v73
	v_cvt_f32_i32_e32 v114, v66
	v_cvt_f32_i32_e32 v115, v67
	v_cvt_f32_i32_e32 v116, v68
	v_cvt_f32_i32_e32 v117, v69
	v_cvt_f32_i32_e32 v82, v62
	v_cvt_f32_i32_e32 v83, v63
	v_cvt_f32_i32_e32 v84, v64
	v_cvt_f32_i32_e32 v85, v65
	v_cvt_f32_i32_e32 v86, v58
	v_cvt_f32_i32_e32 v87, v59
	v_cvt_f32_i32_e32 v88, v60
	v_cvt_f32_i32_e32 v89, v61
	v_cvt_f32_i32_e32 v92, v46
	v_cvt_f32_i32_e32 v93, v47
	v_cvt_f32_i32_e32 v94, v48
	v_cvt_f32_i32_e32 v95, v49
	v_cvt_f32_i32_e32 v96, v38
	v_cvt_f32_i32_e32 v97, v39
	v_cvt_f32_i32_e32 v98, v40
	v_cvt_f32_i32_e32 v99, v41
	v_cvt_f32_i32_e32 v66, v54
	v_cvt_f32_i32_e32 v67, v55
	v_cvt_f32_i32_e32 v68, v56
	v_cvt_f32_i32_e32 v69, v57
	v_cvt_f32_i32_e32 v70, v50
	v_cvt_f32_i32_e32 v71, v51
	v_cvt_f32_i32_e32 v72, v52
	v_cvt_f32_i32_e32 v73, v53
	v_cvt_f32_i32_e32 v74, v30
	v_cvt_f32_i32_e32 v75, v31
	v_cvt_f32_i32_e32 v76, v32
	v_cvt_f32_i32_e32 v77, v33
	v_cvt_f32_i32_e32 v78, v22
	v_cvt_f32_i32_e32 v79, v23
	v_cvt_f32_i32_e32 v80, v24
	v_cvt_f32_i32_e32 v81, v25
	v_cvt_f32_i32_e32 v50, v42
	v_cvt_f32_i32_e32 v51, v43
	v_cvt_f32_i32_e32 v52, v44
	v_cvt_f32_i32_e32 v53, v45
	v_cvt_f32_i32_e32 v54, v34
	v_cvt_f32_i32_e32 v55, v35
	v_cvt_f32_i32_e32 v56, v36
	v_cvt_f32_i32_e32 v57, v37
	v_cvt_f32_i32_e32 v58, v14
	v_cvt_f32_i32_e32 v59, v15
	v_cvt_f32_i32_e32 v60, v16
	v_cvt_f32_i32_e32 v61, v17
	v_cvt_f32_i32_e32 v62, v10
	v_cvt_f32_i32_e32 v63, v11
	v_cvt_f32_i32_e32 v64, v12
	v_cvt_f32_i32_e32 v65, v13
	v_cvt_f32_i32_e32 v34, v26
	v_cvt_f32_i32_e32 v35, v27
	v_cvt_f32_i32_e32 v36, v28
	v_cvt_f32_i32_e32 v37, v29
	v_cvt_f32_i32_e32 v38, v18
	v_cvt_f32_i32_e32 v39, v19
	v_cvt_f32_i32_e32 v40, v20
	v_cvt_f32_i32_e32 v41, v21
	v_cvt_f32_i32_e32 v42, v6
	v_cvt_f32_i32_e32 v43, v7
	v_cvt_f32_i32_e32 v44, v8
	v_cvt_f32_i32_e32 v45, v9
	v_cvt_f32_i32_e32 v46, v2
	v_cvt_f32_i32_e32 v47, v3
	v_cvt_f32_i32_e32 v48, v4
	v_cvt_f32_i32_e32 v49, v5

.LBB0_2949:
	v_add_u32_e32 v138, s60, v188
	ds_read_b128 v[148:151], v138
	ds_read_b128 v[152:155], v138 offset:1024
	ds_read_b128 v[156:159], v138 offset:2048
	ds_read_b128 v[160:163], v138 offset:3072
	v_add_u32_e32 v138, s61, v188
	ds_read_b128 v[164:167], v138
	ds_read_b128 v[168:171], v138 offset:1024
	ds_read_b128 v[172:175], v138 offset:2048
	ds_read_b128 v[176:179], v138 offset:3072
	s_add_i32 s64, s28, 2
	s_add_u32 s65, s26, 0x80
	s_addc_u32 s29, s27, 0
	s_cmp_eq_u32 s58, s28
	s_cselect_b32 s28, s2, s65
	s_cselect_b32 s29, s3, s29
	s_cselect_b32 s67, s25, s35
	s_cselect_b32 s66, s24, s34
	v_lshl_add_u64 v[184:185], s[26:27], 0, v[140:141]
	s_add_i32 m0, s42, 0xc000
	ds_read_b128 v[180:183], v189
	ds_read_b128 v[190:193], v189 offset:1024
	ds_read_b128 v[194:197], v189 offset:2048
	ds_read_b128 v[198:201], v189 offset:3072
	ds_read_b128 v[202:205], v189 offset:4096
	ds_read_b128 v[206:209], v189 offset:5120
	ds_read_b128 v[210:213], v189 offset:6144
	ds_read_b128 v[214:217], v189 offset:7168
	global_load_lds_dwordx4 v[184:185], off
	v_lshl_add_u64 v[184:185], s[26:27], 0, v[142:143]
	s_add_i32 m0, s42, 0xe000
	s_nop 0
	global_load_lds_dwordx4 v[184:185], off
	s_waitcnt vmcnt(8)
	s_waitcnt lgkmcnt(0)
	s_barrier
	s_setprio 1
	s_waitcnt lgkmcnt(0)
	v_mfma_i32_16x16x64_i8 v[126:129], v[148:151], v[180:183], v[126:129]
	v_mfma_i32_16x16x64_i8 v[122:125], v[156:159], v[180:183], v[122:125]
	v_mfma_i32_16x16x64_i8 v[118:121], v[148:151], v[194:197], v[118:121]
	v_mfma_i32_16x16x64_i8 v[114:117], v[156:159], v[194:197], v[114:117]
	v_mfma_i32_16x16x64_i8 v[106:109], v[148:151], v[202:205], v[106:109]
	v_mfma_i32_16x16x64_i8 v[98:101], v[156:159], v[202:205], v[98:101]
	v_mfma_i32_16x16x64_i8 v[90:93], v[148:151], v[210:213], v[90:93]
	v_mfma_i32_16x16x64_i8 v[82:85], v[156:159], v[210:213], v[82:85]
	v_mfma_i32_16x16x64_i8 v[126:129], v[152:155], v[190:193], v[126:129]
	v_mfma_i32_16x16x64_i8 v[122:125], v[160:163], v[190:193], v[122:125]
	v_mfma_i32_16x16x64_i8 v[118:121], v[152:155], v[198:201], v[118:121]
	v_mfma_i32_16x16x64_i8 v[114:117], v[160:163], v[198:201], v[114:117]
	v_mfma_i32_16x16x64_i8 v[106:109], v[152:155], v[206:209], v[106:109]
	v_mfma_i32_16x16x64_i8 v[98:101], v[160:163], v[206:209], v[98:101]
	v_mfma_i32_16x16x64_i8 v[90:93], v[152:155], v[214:217], v[90:93]
	v_mfma_i32_16x16x64_i8 v[82:85], v[160:163], v[214:217], v[82:85]
	s_setprio 0
	s_setprio 1
	v_mfma_i32_16x16x64_i8 v[110:113], v[164:167], v[180:183], v[110:113]
	v_mfma_i32_16x16x64_i8 v[102:105], v[172:175], v[180:183], v[102:105]
	v_mfma_i32_16x16x64_i8 v[94:97], v[164:167], v[194:197], v[94:97]
	v_mfma_i32_16x16x64_i8 v[86:89], v[172:175], v[194:197], v[86:89]
	v_mfma_i32_16x16x64_i8 v[78:81], v[164:167], v[202:205], v[78:81]
	v_mfma_i32_16x16x64_i8 v[74:77], v[172:175], v[202:205], v[74:77]
	v_mfma_i32_16x16x64_i8 v[70:73], v[164:167], v[210:213], v[70:73]
	v_mfma_i32_16x16x64_i8 v[66:69], v[172:175], v[210:213], v[66:69]
	v_mfma_i32_16x16x64_i8 v[110:113], v[168:171], v[190:193], v[110:113]
	v_mfma_i32_16x16x64_i8 v[102:105], v[176:179], v[190:193], v[102:105]
	v_mfma_i32_16x16x64_i8 v[94:97], v[168:171], v[198:201], v[94:97]
	v_mfma_i32_16x16x64_i8 v[86:89], v[176:179], v[198:201], v[86:89]
	v_mfma_i32_16x16x64_i8 v[78:81], v[168:171], v[206:209], v[78:81]
	v_mfma_i32_16x16x64_i8 v[74:77], v[176:179], v[206:209], v[74:77]
	v_mfma_i32_16x16x64_i8 v[70:73], v[168:171], v[214:217], v[70:73]
	v_mfma_i32_16x16x64_i8 v[66:69], v[176:179], v[214:217], v[66:69]
	s_setprio 0
	s_barrier
	s_add_i32 s65, s60, s41
	v_lshl_add_u64 v[184:185], s[66:67], 0, v[132:133]
	s_mov_b32 m0, s65
	ds_read_b128 v[180:183], v189 offset:16384
	ds_read_b128 v[190:193], v189 offset:17408
	ds_read_b128 v[194:197], v189 offset:18432
	ds_read_b128 v[198:201], v189 offset:19456
	ds_read_b128 v[202:205], v189 offset:20480
	ds_read_b128 v[206:209], v189 offset:21504
	ds_read_b128 v[210:213], v189 offset:22528
	ds_read_b128 v[214:217], v189 offset:23552
	global_load_lds_dwordx4 v[184:185], off
	s_add_i32 m0, s65, 0x2000
	v_lshl_add_u64 v[218:219], s[66:67], 0, v[136:137]
	s_add_u32 s66, s66, s6
	s_addc_u32 s67, s67, s7
	s_add_i32 s65, s61, s41
	global_load_lds_dwordx4 v[218:219], off
	v_lshl_add_u64 v[220:221], s[66:67], 0, v[132:133]
	s_mov_b32 m0, s65
	v_lshl_add_u64 v[222:223], s[66:67], 0, v[136:137]
	global_load_lds_dwordx4 v[220:221], off
	s_add_i32 m0, s65, 0x2000
	v_lshl_add_u64 v[224:225], s[28:29], 0, v[130:131]
	global_load_lds_dwordx4 v[222:223], off
	s_waitcnt vmcnt(6)
	s_waitcnt lgkmcnt(0)
	s_barrier
	s_setprio 1
	s_waitcnt lgkmcnt(0)
	v_mfma_i32_16x16x64_i8 v[62:65], v[148:151], v[180:183], v[62:65]
	v_mfma_i32_16x16x64_i8 v[58:61], v[156:159], v[180:183], v[58:61]
	v_mfma_i32_16x16x64_i8 v[54:57], v[148:151], v[194:197], v[54:57]
	v_mfma_i32_16x16x64_i8 v[50:53], v[156:159], v[194:197], v[50:53]
	s_mov_b32 m0, s42
	v_lshl_add_u64 v[226:227], s[28:29], 0, v[134:135]
	global_load_lds_dwordx4 v[224:225], off
	v_mfma_i32_16x16x64_i8 v[42:45], v[148:151], v[202:205], v[42:45]
	v_mfma_i32_16x16x64_i8 v[34:37], v[156:159], v[202:205], v[34:37]
	v_mfma_i32_16x16x64_i8 v[26:29], v[148:151], v[210:213], v[26:29]
	v_mfma_i32_16x16x64_i8 v[18:21], v[156:159], v[210:213], v[18:21]
	v_mfma_i32_16x16x64_i8 v[62:65], v[152:155], v[190:193], v[62:65]
	v_mfma_i32_16x16x64_i8 v[58:61], v[160:163], v[190:193], v[58:61]
	v_mfma_i32_16x16x64_i8 v[54:57], v[152:155], v[198:201], v[54:57]
	v_mfma_i32_16x16x64_i8 v[50:53], v[160:163], v[198:201], v[50:53]
	v_mfma_i32_16x16x64_i8 v[42:45], v[152:155], v[206:209], v[42:45]
	v_mfma_i32_16x16x64_i8 v[34:37], v[160:163], v[206:209], v[34:37]
	v_mfma_i32_16x16x64_i8 v[26:29], v[152:155], v[214:217], v[26:29]
	v_mfma_i32_16x16x64_i8 v[18:21], v[160:163], v[214:217], v[18:21]
	s_setprio 0
	s_setprio 1
	v_mfma_i32_16x16x64_i8 v[46:49], v[164:167], v[180:183], v[46:49]
	v_mfma_i32_16x16x64_i8 v[38:41], v[172:175], v[180:183], v[38:41]
	v_mfma_i32_16x16x64_i8 v[30:33], v[164:167], v[194:197], v[30:33]
	v_mfma_i32_16x16x64_i8 v[22:25], v[172:175], v[194:197], v[22:25]
	s_mov_b32 m0, s43
	s_nop 0
	global_load_lds_dwordx4 v[226:227], off
	v_mfma_i32_16x16x64_i8 v[14:17], v[164:167], v[202:205], v[14:17]
	v_mfma_i32_16x16x64_i8 v[10:13], v[172:175], v[202:205], v[10:13]
	v_mfma_i32_16x16x64_i8 v[6:9], v[164:167], v[210:213], v[6:9]
	v_mfma_i32_16x16x64_i8 v[2:5], v[172:175], v[210:213], v[2:5]
	v_mfma_i32_16x16x64_i8 v[46:49], v[168:171], v[190:193], v[46:49]
	v_mfma_i32_16x16x64_i8 v[38:41], v[176:179], v[190:193], v[38:41]
	v_mfma_i32_16x16x64_i8 v[30:33], v[168:171], v[198:201], v[30:33]
	v_mfma_i32_16x16x64_i8 v[22:25], v[176:179], v[198:201], v[22:25]
	v_mfma_i32_16x16x64_i8 v[14:17], v[168:171], v[206:209], v[14:17]
	v_mfma_i32_16x16x64_i8 v[10:13], v[176:179], v[206:209], v[10:13]
	v_mfma_i32_16x16x64_i8 v[6:9], v[168:171], v[214:217], v[6:9]
	v_mfma_i32_16x16x64_i8 v[2:5], v[176:179], v[214:217], v[2:5]
	s_setprio 0
	s_barrier
	s_add_i32 s65, 0, 0x18000
	v_add_u32_e32 v138, s65, v188
	s_add_i32 s66, 0, 0x1c000
	ds_read_b128 v[148:151], v138
	ds_read_b128 v[152:155], v138 offset:1024
	ds_read_b128 v[156:159], v138 offset:2048
	ds_read_b128 v[160:163], v138 offset:3072
	v_add_u32_e32 v138, s66, v188
	ds_read_b128 v[164:167], v138
	ds_read_b128 v[168:171], v138 offset:1024
	ds_read_b128 v[172:175], v138 offset:2048
	ds_read_b128 v[176:179], v138 offset:3072
	s_add_u32 s28, s28, s6
	s_addc_u32 s29, s29, s7
	s_mov_b32 m0, s44
	v_lshl_add_u64 v[228:229], s[28:29], 0, v[130:131]
	ds_read_b128 v[180:183], v189 offset:32768
	ds_read_b128 v[190:193], v189 offset:33792
	ds_read_b128 v[194:197], v189 offset:34816
	ds_read_b128 v[198:201], v189 offset:35840
	ds_read_b128 v[202:205], v189 offset:36864
	ds_read_b128 v[206:209], v189 offset:37888
	ds_read_b128 v[210:213], v189 offset:38912
	ds_read_b128 v[214:217], v189 offset:39936
	global_load_lds_dwordx4 v[228:229], off
	v_lshl_add_u64 v[228:229], s[28:29], 0, v[134:135]
	s_mov_b32 m0, s45
	s_nop 0
	global_load_lds_dwordx4 v[228:229], off
	s_waitcnt vmcnt(8)
	s_waitcnt lgkmcnt(0)
	s_barrier
	s_setprio 1
	s_waitcnt lgkmcnt(0)
	v_mfma_i32_16x16x64_i8 v[126:129], v[148:151], v[180:183], v[126:129]
	v_mfma_i32_16x16x64_i8 v[122:125], v[156:159], v[180:183], v[122:125]
	v_mfma_i32_16x16x64_i8 v[118:121], v[148:151], v[194:197], v[118:121]
	v_mfma_i32_16x16x64_i8 v[114:117], v[156:159], v[194:197], v[114:117]
	v_mfma_i32_16x16x64_i8 v[106:109], v[148:151], v[202:205], v[106:109]
	v_mfma_i32_16x16x64_i8 v[98:101], v[156:159], v[202:205], v[98:101]
	v_mfma_i32_16x16x64_i8 v[90:93], v[148:151], v[210:213], v[90:93]
	v_mfma_i32_16x16x64_i8 v[82:85], v[156:159], v[210:213], v[82:85]
	v_mfma_i32_16x16x64_i8 v[126:129], v[152:155], v[190:193], v[126:129]
	v_mfma_i32_16x16x64_i8 v[122:125], v[160:163], v[190:193], v[122:125]
	v_mfma_i32_16x16x64_i8 v[118:121], v[152:155], v[198:201], v[118:121]
	v_mfma_i32_16x16x64_i8 v[114:117], v[160:163], v[198:201], v[114:117]
	v_mfma_i32_16x16x64_i8 v[106:109], v[152:155], v[206:209], v[106:109]
	v_mfma_i32_16x16x64_i8 v[98:101], v[160:163], v[206:209], v[98:101]
	v_mfma_i32_16x16x64_i8 v[90:93], v[152:155], v[214:217], v[90:93]
	v_mfma_i32_16x16x64_i8 v[82:85], v[160:163], v[214:217], v[82:85]
	s_setprio 0
	s_setprio 1
	v_mfma_i32_16x16x64_i8 v[110:113], v[164:167], v[180:183], v[110:113]
	v_mfma_i32_16x16x64_i8 v[102:105], v[172:175], v[180:183], v[102:105]
	v_mfma_i32_16x16x64_i8 v[94:97], v[164:167], v[194:197], v[94:97]
	v_mfma_i32_16x16x64_i8 v[86:89], v[172:175], v[194:197], v[86:89]
	v_mfma_i32_16x16x64_i8 v[78:81], v[164:167], v[202:205], v[78:81]
	v_mfma_i32_16x16x64_i8 v[74:77], v[172:175], v[202:205], v[74:77]
	v_mfma_i32_16x16x64_i8 v[70:73], v[164:167], v[210:213], v[70:73]
	v_mfma_i32_16x16x64_i8 v[66:69], v[172:175], v[210:213], v[66:69]
	v_mfma_i32_16x16x64_i8 v[110:113], v[168:171], v[190:193], v[110:113]
	v_mfma_i32_16x16x64_i8 v[102:105], v[176:179], v[190:193], v[102:105]
	v_mfma_i32_16x16x64_i8 v[94:97], v[168:171], v[198:201], v[94:97]
	v_mfma_i32_16x16x64_i8 v[86:89], v[176:179], v[198:201], v[86:89]
	v_mfma_i32_16x16x64_i8 v[78:81], v[168:171], v[206:209], v[78:81]
	v_mfma_i32_16x16x64_i8 v[74:77], v[176:179], v[206:209], v[74:77]
	v_mfma_i32_16x16x64_i8 v[70:73], v[168:171], v[214:217], v[70:73]
	v_mfma_i32_16x16x64_i8 v[66:69], v[176:179], v[214:217], v[66:69]
	s_setprio 0
	s_barrier
	s_add_i32 s28, s65, s41
	v_lshl_add_u64 v[184:185], v[184:185], 0, s[18:19]
	s_mov_b32 m0, s28
	ds_read_b128 v[180:183], v189 offset:49152
	ds_read_b128 v[190:193], v189 offset:50176
	ds_read_b128 v[194:197], v189 offset:51200
	ds_read_b128 v[198:201], v189 offset:52224
	ds_read_b128 v[202:205], v189 offset:53248
	ds_read_b128 v[206:209], v189 offset:54272
	ds_read_b128 v[210:213], v189 offset:55296
	ds_read_b128 v[214:217], v189 offset:56320
	global_load_lds_dwordx4 v[184:185], off
	v_lshl_add_u64 v[184:185], v[218:219], 0, s[18:19]
	s_add_i32 m0, s28, 0x2000
	s_add_i32 s28, s66, s41
	global_load_lds_dwordx4 v[184:185], off
	v_lshl_add_u64 v[184:185], v[220:221], 0, s[18:19]
	s_mov_b32 m0, s28
	s_nop 0
	global_load_lds_dwordx4 v[184:185], off
	v_lshl_add_u64 v[184:185], v[222:223], 0, s[18:19]
	s_add_i32 m0, s28, 0x2000
	s_nop 0
	global_load_lds_dwordx4 v[184:185], off
	s_waitcnt vmcnt(6)
	s_waitcnt lgkmcnt(0)
	s_barrier
	s_setprio 1
	s_waitcnt lgkmcnt(0)
	v_mfma_i32_16x16x64_i8 v[62:65], v[148:151], v[180:183], v[62:65]
	v_mfma_i32_16x16x64_i8 v[58:61], v[156:159], v[180:183], v[58:61]
	v_mfma_i32_16x16x64_i8 v[54:57], v[148:151], v[194:197], v[54:57]
	v_mfma_i32_16x16x64_i8 v[50:53], v[156:159], v[194:197], v[50:53]
	v_lshl_add_u64 v[184:185], v[224:225], 0, s[18:19]
	s_mov_b32 m0, s51
	s_nop 0
	global_load_lds_dwordx4 v[184:185], off
	v_mfma_i32_16x16x64_i8 v[42:45], v[148:151], v[202:205], v[42:45]
	v_mfma_i32_16x16x64_i8 v[34:37], v[156:159], v[202:205], v[34:37]
	v_mfma_i32_16x16x64_i8 v[26:29], v[148:151], v[210:213], v[26:29]
	v_mfma_i32_16x16x64_i8 v[18:21], v[156:159], v[210:213], v[18:21]
	v_mfma_i32_16x16x64_i8 v[62:65], v[152:155], v[190:193], v[62:65]
	v_mfma_i32_16x16x64_i8 v[58:61], v[160:163], v[190:193], v[58:61]
	v_mfma_i32_16x16x64_i8 v[54:57], v[152:155], v[198:201], v[54:57]
	v_mfma_i32_16x16x64_i8 v[50:53], v[160:163], v[198:201], v[50:53]
	v_mfma_i32_16x16x64_i8 v[42:45], v[152:155], v[206:209], v[42:45]
	v_mfma_i32_16x16x64_i8 v[34:37], v[160:163], v[206:209], v[34:37]
	v_mfma_i32_16x16x64_i8 v[26:29], v[152:155], v[214:217], v[26:29]
	v_mfma_i32_16x16x64_i8 v[18:21], v[160:163], v[214:217], v[18:21]
	s_setprio 0
	s_setprio 1
	v_mfma_i32_16x16x64_i8 v[46:49], v[164:167], v[180:183], v[46:49]
	v_mfma_i32_16x16x64_i8 v[38:41], v[172:175], v[180:183], v[38:41]
	v_mfma_i32_16x16x64_i8 v[30:33], v[164:167], v[194:197], v[30:33]
	v_mfma_i32_16x16x64_i8 v[22:25], v[172:175], v[194:197], v[22:25]
	v_lshl_add_u64 v[184:185], v[226:227], 0, s[18:19]
	s_mov_b32 m0, s54
	s_nop 0
	global_load_lds_dwordx4 v[184:185], off
	v_mfma_i32_16x16x64_i8 v[14:17], v[164:167], v[202:205], v[14:17]
	v_mfma_i32_16x16x64_i8 v[10:13], v[172:175], v[202:205], v[10:13]
	v_mfma_i32_16x16x64_i8 v[6:9], v[164:167], v[210:213], v[6:9]
	v_mfma_i32_16x16x64_i8 v[2:5], v[172:175], v[210:213], v[2:5]
	v_mfma_i32_16x16x64_i8 v[46:49], v[168:171], v[190:193], v[46:49]
	v_mfma_i32_16x16x64_i8 v[38:41], v[176:179], v[190:193], v[38:41]
	v_mfma_i32_16x16x64_i8 v[30:33], v[168:171], v[198:201], v[30:33]
	v_mfma_i32_16x16x64_i8 v[22:25], v[176:179], v[198:201], v[22:25]
	v_mfma_i32_16x16x64_i8 v[14:17], v[168:171], v[206:209], v[14:17]
	v_mfma_i32_16x16x64_i8 v[10:13], v[176:179], v[206:209], v[10:13]
	v_mfma_i32_16x16x64_i8 v[6:9], v[168:171], v[214:217], v[6:9]
	v_mfma_i32_16x16x64_i8 v[2:5], v[176:179], v[214:217], v[2:5]
	s_setprio 0
	s_barrier
	s_add_u32 s26, s26, 0x100
	s_addc_u32 s27, s27, 0
	s_add_u32 s34, s34, 0x100
	s_addc_u32 s35, s35, 0
	s_cmp_ge_i32 s64, s55
	s_mov_b32 s28, s64
	s_cbranch_scc0 .LBB0_2949
	v_cvt_f32_i32_e32 v172, v126
	v_cvt_f32_i32_e32 v173, v127
	v_cvt_f32_i32_e32 v170, v128
	v_cvt_f32_i32_e32 v171, v129
	v_cvt_f32_i32_e32 v174, v122
	v_cvt_f32_i32_e32 v175, v123
	v_cvt_f32_i32_e32 v176, v124
	v_cvt_f32_i32_e32 v177, v125
	v_cvt_f32_i32_e32 v180, v110
	v_cvt_f32_i32_e32 v181, v111
	v_cvt_f32_i32_e32 v182, v112
	v_cvt_f32_i32_e32 v183, v113
	v_cvt_f32_i32_e32 v178, v102
	v_cvt_f32_i32_e32 v179, v103
	v_cvt_f32_i32_e32 v184, v104
	v_cvt_f32_i32_e32 v185, v105
	v_cvt_f32_i32_e32 v152, v118
	v_cvt_f32_i32_e32 v153, v119
	v_cvt_f32_i32_e32 v154, v120
	v_cvt_f32_i32_e32 v155, v121
	v_cvt_f32_i32_e32 v156, v114
	v_cvt_f32_i32_e32 v157, v115
	v_cvt_f32_i32_e32 v158, v116
	v_cvt_f32_i32_e32 v159, v117
	v_cvt_f32_i32_e32 v160, v94
	v_cvt_f32_i32_e32 v161, v95
	v_cvt_f32_i32_e32 v162, v96
	v_cvt_f32_i32_e32 v163, v97
	v_cvt_f32_i32_e32 v164, v86
	v_cvt_f32_i32_e32 v165, v87
	v_cvt_f32_i32_e32 v166, v88
	v_cvt_f32_i32_e32 v167, v89
	v_cvt_f32_i32_e32 v118, v106
	v_cvt_f32_i32_e32 v119, v107
	v_cvt_f32_i32_e32 v120, v108
	v_cvt_f32_i32_e32 v121, v109
	v_cvt_f32_i32_e32 v122, v98
	v_cvt_f32_i32_e32 v123, v99
	v_cvt_f32_i32_e32 v124, v100
	v_cvt_f32_i32_e32 v125, v101
	v_cvt_f32_i32_e32 v126, v78
	v_cvt_f32_i32_e32 v127, v79
	v_cvt_f32_i32_e32 v128, v80
	v_cvt_f32_i32_e32 v129, v81
	v_cvt_f32_i32_e32 v148, v74
	v_cvt_f32_i32_e32 v149, v75
	v_cvt_f32_i32_e32 v150, v76
	v_cvt_f32_i32_e32 v151, v77
	v_cvt_f32_i32_e32 v102, v90
	v_cvt_f32_i32_e32 v103, v91
	v_cvt_f32_i32_e32 v104, v92
	v_cvt_f32_i32_e32 v105, v93
	v_cvt_f32_i32_e32 v106, v82
	v_cvt_f32_i32_e32 v107, v83
	v_cvt_f32_i32_e32 v108, v84
	v_cvt_f32_i32_e32 v109, v85
	v_cvt_f32_i32_e32 v110, v70
	v_cvt_f32_i32_e32 v111, v71
	v_cvt_f32_i32_e32 v112, v72
	v_cvt_f32_i32_e32 v113, v73
	v_cvt_f32_i32_e32 v114, v66
	v_cvt_f32_i32_e32 v115, v67
	v_cvt_f32_i32_e32 v116, v68
	v_cvt_f32_i32_e32 v117, v69
	v_cvt_f32_i32_e32 v82, v62
	v_cvt_f32_i32_e32 v83, v63
	v_cvt_f32_i32_e32 v84, v64
	v_cvt_f32_i32_e32 v85, v65
	v_cvt_f32_i32_e32 v86, v58
	v_cvt_f32_i32_e32 v87, v59
	v_cvt_f32_i32_e32 v88, v60
	v_cvt_f32_i32_e32 v89, v61
	v_cvt_f32_i32_e32 v92, v46
	v_cvt_f32_i32_e32 v93, v47
	v_cvt_f32_i32_e32 v94, v48
	v_cvt_f32_i32_e32 v95, v49
	v_cvt_f32_i32_e32 v96, v38
	v_cvt_f32_i32_e32 v97, v39
	v_cvt_f32_i32_e32 v98, v40
	v_cvt_f32_i32_e32 v99, v41
	v_cvt_f32_i32_e32 v66, v54
	v_cvt_f32_i32_e32 v67, v55
	v_cvt_f32_i32_e32 v68, v56
	v_cvt_f32_i32_e32 v69, v57
	v_cvt_f32_i32_e32 v70, v50
	v_cvt_f32_i32_e32 v71, v51
	v_cvt_f32_i32_e32 v72, v52
	v_cvt_f32_i32_e32 v73, v53
	v_cvt_f32_i32_e32 v74, v30
	v_cvt_f32_i32_e32 v75, v31
	v_cvt_f32_i32_e32 v76, v32
	v_cvt_f32_i32_e32 v77, v33
	v_cvt_f32_i32_e32 v78, v22
	v_cvt_f32_i32_e32 v79, v23
	v_cvt_f32_i32_e32 v80, v24
	v_cvt_f32_i32_e32 v81, v25
	v_cvt_f32_i32_e32 v50, v42
	v_cvt_f32_i32_e32 v51, v43
	v_cvt_f32_i32_e32 v52, v44
	v_cvt_f32_i32_e32 v53, v45
	v_cvt_f32_i32_e32 v54, v34
	v_cvt_f32_i32_e32 v55, v35
	v_cvt_f32_i32_e32 v56, v36
	v_cvt_f32_i32_e32 v57, v37
	v_cvt_f32_i32_e32 v58, v14
	v_cvt_f32_i32_e32 v59, v15
	v_cvt_f32_i32_e32 v60, v16
	v_cvt_f32_i32_e32 v61, v17
	v_cvt_f32_i32_e32 v62, v10
	v_cvt_f32_i32_e32 v63, v11
	v_cvt_f32_i32_e32 v64, v12
	v_cvt_f32_i32_e32 v65, v13
	v_cvt_f32_i32_e32 v34, v26
	v_cvt_f32_i32_e32 v35, v27
	v_cvt_f32_i32_e32 v36, v28
	v_cvt_f32_i32_e32 v37, v29
	v_cvt_f32_i32_e32 v38, v18
	v_cvt_f32_i32_e32 v39, v19
	v_cvt_f32_i32_e32 v40, v20
	v_cvt_f32_i32_e32 v41, v21
	v_cvt_f32_i32_e32 v42, v6
	v_cvt_f32_i32_e32 v43, v7
	v_cvt_f32_i32_e32 v44, v8
	v_cvt_f32_i32_e32 v45, v9
	v_cvt_f32_i32_e32 v46, v2
	v_cvt_f32_i32_e32 v47, v3
	v_cvt_f32_i32_e32 v48, v4
	v_cvt_f32_i32_e32 v49, v5

.LBB0_3798:
	v_add_u32_e32 v138, s56, v188
	ds_read_b128 v[148:151], v138
	ds_read_b128 v[152:155], v138 offset:1024
	ds_read_b128 v[156:159], v138 offset:2048
	ds_read_b128 v[160:163], v138 offset:3072
	v_add_u32_e32 v138, s57, v188
	ds_read_b128 v[164:167], v138
	ds_read_b128 v[168:171], v138 offset:1024
	ds_read_b128 v[172:175], v138 offset:2048
	ds_read_b128 v[176:179], v138 offset:3072
	s_add_i32 s60, s28, 2
	s_add_u32 s61, s26, 0x80
	s_addc_u32 s29, s27, 0
	s_cmp_eq_u32 s54, s28
	s_cselect_b32 s28, s2, s61
	s_cselect_b32 s29, s3, s29
	s_cselect_b32 s63, s25, s35
	s_cselect_b32 s62, s24, s34
	v_lshl_add_u64 v[184:185], s[26:27], 0, v[140:141]
	s_add_i32 m0, s42, 0xc000
	ds_read_b128 v[180:183], v189
	ds_read_b128 v[190:193], v189 offset:1024
	ds_read_b128 v[194:197], v189 offset:2048
	ds_read_b128 v[198:201], v189 offset:3072
	ds_read_b128 v[202:205], v189 offset:4096
	ds_read_b128 v[206:209], v189 offset:5120
	ds_read_b128 v[210:213], v189 offset:6144
	ds_read_b128 v[214:217], v189 offset:7168
	global_load_lds_dwordx4 v[184:185], off
	v_lshl_add_u64 v[184:185], s[26:27], 0, v[142:143]
	s_add_i32 m0, s42, 0xe000
	s_nop 0
	global_load_lds_dwordx4 v[184:185], off
	s_waitcnt vmcnt(8)
	s_waitcnt lgkmcnt(0)
	s_barrier
	s_setprio 1
	s_waitcnt lgkmcnt(0)
	v_mfma_i32_16x16x64_i8 v[126:129], v[148:151], v[180:183], v[126:129]
	v_mfma_i32_16x16x64_i8 v[122:125], v[156:159], v[180:183], v[122:125]
	v_mfma_i32_16x16x64_i8 v[118:121], v[148:151], v[194:197], v[118:121]
	v_mfma_i32_16x16x64_i8 v[114:117], v[156:159], v[194:197], v[114:117]
	v_mfma_i32_16x16x64_i8 v[106:109], v[148:151], v[202:205], v[106:109]
	v_mfma_i32_16x16x64_i8 v[98:101], v[156:159], v[202:205], v[98:101]
	v_mfma_i32_16x16x64_i8 v[90:93], v[148:151], v[210:213], v[90:93]
	v_mfma_i32_16x16x64_i8 v[82:85], v[156:159], v[210:213], v[82:85]
	v_mfma_i32_16x16x64_i8 v[126:129], v[152:155], v[190:193], v[126:129]
	v_mfma_i32_16x16x64_i8 v[122:125], v[160:163], v[190:193], v[122:125]
	v_mfma_i32_16x16x64_i8 v[118:121], v[152:155], v[198:201], v[118:121]
	v_mfma_i32_16x16x64_i8 v[114:117], v[160:163], v[198:201], v[114:117]
	v_mfma_i32_16x16x64_i8 v[106:109], v[152:155], v[206:209], v[106:109]
	v_mfma_i32_16x16x64_i8 v[98:101], v[160:163], v[206:209], v[98:101]
	v_mfma_i32_16x16x64_i8 v[90:93], v[152:155], v[214:217], v[90:93]
	v_mfma_i32_16x16x64_i8 v[82:85], v[160:163], v[214:217], v[82:85]
	s_setprio 0
	s_setprio 1
	v_mfma_i32_16x16x64_i8 v[110:113], v[164:167], v[180:183], v[110:113]
	v_mfma_i32_16x16x64_i8 v[102:105], v[172:175], v[180:183], v[102:105]
	v_mfma_i32_16x16x64_i8 v[94:97], v[164:167], v[194:197], v[94:97]
	v_mfma_i32_16x16x64_i8 v[86:89], v[172:175], v[194:197], v[86:89]
	v_mfma_i32_16x16x64_i8 v[78:81], v[164:167], v[202:205], v[78:81]
	v_mfma_i32_16x16x64_i8 v[74:77], v[172:175], v[202:205], v[74:77]
	v_mfma_i32_16x16x64_i8 v[70:73], v[164:167], v[210:213], v[70:73]
	v_mfma_i32_16x16x64_i8 v[66:69], v[172:175], v[210:213], v[66:69]
	v_mfma_i32_16x16x64_i8 v[110:113], v[168:171], v[190:193], v[110:113]
	v_mfma_i32_16x16x64_i8 v[102:105], v[176:179], v[190:193], v[102:105]
	v_mfma_i32_16x16x64_i8 v[94:97], v[168:171], v[198:201], v[94:97]
	v_mfma_i32_16x16x64_i8 v[86:89], v[176:179], v[198:201], v[86:89]
	v_mfma_i32_16x16x64_i8 v[78:81], v[168:171], v[206:209], v[78:81]
	v_mfma_i32_16x16x64_i8 v[74:77], v[176:179], v[206:209], v[74:77]
	v_mfma_i32_16x16x64_i8 v[70:73], v[168:171], v[214:217], v[70:73]
	v_mfma_i32_16x16x64_i8 v[66:69], v[176:179], v[214:217], v[66:69]
	s_setprio 0
	s_barrier
	s_add_i32 s61, s56, s41
	v_lshl_add_u64 v[184:185], s[62:63], 0, v[132:133]
	s_mov_b32 m0, s61
	ds_read_b128 v[180:183], v189 offset:16384
	ds_read_b128 v[190:193], v189 offset:17408
	ds_read_b128 v[194:197], v189 offset:18432
	ds_read_b128 v[198:201], v189 offset:19456
	ds_read_b128 v[202:205], v189 offset:20480
	ds_read_b128 v[206:209], v189 offset:21504
	ds_read_b128 v[210:213], v189 offset:22528
	ds_read_b128 v[214:217], v189 offset:23552
	global_load_lds_dwordx4 v[184:185], off
	s_add_i32 m0, s61, 0x2000
	v_lshl_add_u64 v[218:219], s[62:63], 0, v[136:137]
	s_add_u32 s62, s62, s6
	s_addc_u32 s63, s63, s7
	s_add_i32 s61, s57, s41
	global_load_lds_dwordx4 v[218:219], off
	v_lshl_add_u64 v[220:221], s[62:63], 0, v[132:133]
	s_mov_b32 m0, s61
	v_lshl_add_u64 v[222:223], s[62:63], 0, v[136:137]
	global_load_lds_dwordx4 v[220:221], off
	s_add_i32 m0, s61, 0x2000
	v_lshl_add_u64 v[224:225], s[28:29], 0, v[130:131]
	global_load_lds_dwordx4 v[222:223], off
	s_waitcnt vmcnt(6)
	s_waitcnt lgkmcnt(0)
	s_barrier
	s_setprio 1
	s_waitcnt lgkmcnt(0)
	v_mfma_i32_16x16x64_i8 v[62:65], v[148:151], v[180:183], v[62:65]
	v_mfma_i32_16x16x64_i8 v[58:61], v[156:159], v[180:183], v[58:61]
	v_mfma_i32_16x16x64_i8 v[54:57], v[148:151], v[194:197], v[54:57]
	v_mfma_i32_16x16x64_i8 v[50:53], v[156:159], v[194:197], v[50:53]
	s_mov_b32 m0, s42
	v_lshl_add_u64 v[226:227], s[28:29], 0, v[134:135]
	global_load_lds_dwordx4 v[224:225], off
	v_mfma_i32_16x16x64_i8 v[42:45], v[148:151], v[202:205], v[42:45]
	v_mfma_i32_16x16x64_i8 v[34:37], v[156:159], v[202:205], v[34:37]
	v_mfma_i32_16x16x64_i8 v[26:29], v[148:151], v[210:213], v[26:29]
	v_mfma_i32_16x16x64_i8 v[18:21], v[156:159], v[210:213], v[18:21]
	v_mfma_i32_16x16x64_i8 v[62:65], v[152:155], v[190:193], v[62:65]
	v_mfma_i32_16x16x64_i8 v[58:61], v[160:163], v[190:193], v[58:61]
	v_mfma_i32_16x16x64_i8 v[54:57], v[152:155], v[198:201], v[54:57]
	v_mfma_i32_16x16x64_i8 v[50:53], v[160:163], v[198:201], v[50:53]
	v_mfma_i32_16x16x64_i8 v[42:45], v[152:155], v[206:209], v[42:45]
	v_mfma_i32_16x16x64_i8 v[34:37], v[160:163], v[206:209], v[34:37]
	v_mfma_i32_16x16x64_i8 v[26:29], v[152:155], v[214:217], v[26:29]
	v_mfma_i32_16x16x64_i8 v[18:21], v[160:163], v[214:217], v[18:21]
	s_setprio 0
	s_setprio 1
	v_mfma_i32_16x16x64_i8 v[46:49], v[164:167], v[180:183], v[46:49]
	v_mfma_i32_16x16x64_i8 v[38:41], v[172:175], v[180:183], v[38:41]
	v_mfma_i32_16x16x64_i8 v[30:33], v[164:167], v[194:197], v[30:33]
	v_mfma_i32_16x16x64_i8 v[22:25], v[172:175], v[194:197], v[22:25]
	s_mov_b32 m0, s43
	s_nop 0
	global_load_lds_dwordx4 v[226:227], off
	v_mfma_i32_16x16x64_i8 v[14:17], v[164:167], v[202:205], v[14:17]
	v_mfma_i32_16x16x64_i8 v[10:13], v[172:175], v[202:205], v[10:13]
	v_mfma_i32_16x16x64_i8 v[6:9], v[164:167], v[210:213], v[6:9]
	v_mfma_i32_16x16x64_i8 v[2:5], v[172:175], v[210:213], v[2:5]
	v_mfma_i32_16x16x64_i8 v[46:49], v[168:171], v[190:193], v[46:49]
	v_mfma_i32_16x16x64_i8 v[38:41], v[176:179], v[190:193], v[38:41]
	v_mfma_i32_16x16x64_i8 v[30:33], v[168:171], v[198:201], v[30:33]
	v_mfma_i32_16x16x64_i8 v[22:25], v[176:179], v[198:201], v[22:25]
	v_mfma_i32_16x16x64_i8 v[14:17], v[168:171], v[206:209], v[14:17]
	v_mfma_i32_16x16x64_i8 v[10:13], v[176:179], v[206:209], v[10:13]
	v_mfma_i32_16x16x64_i8 v[6:9], v[168:171], v[214:217], v[6:9]
	v_mfma_i32_16x16x64_i8 v[2:5], v[176:179], v[214:217], v[2:5]
	s_setprio 0
	s_barrier
	s_add_i32 s61, 0, 0x18000
	v_add_u32_e32 v138, s61, v188
	s_add_i32 s62, 0, 0x1c000
	ds_read_b128 v[148:151], v138
	ds_read_b128 v[152:155], v138 offset:1024
	ds_read_b128 v[156:159], v138 offset:2048
	ds_read_b128 v[160:163], v138 offset:3072
	v_add_u32_e32 v138, s62, v188
	ds_read_b128 v[164:167], v138
	ds_read_b128 v[168:171], v138 offset:1024
	ds_read_b128 v[172:175], v138 offset:2048
	ds_read_b128 v[176:179], v138 offset:3072
	s_add_u32 s28, s28, s6
	s_addc_u32 s29, s29, s7
	s_mov_b32 m0, s44
	v_lshl_add_u64 v[228:229], s[28:29], 0, v[130:131]
	ds_read_b128 v[180:183], v189 offset:32768
	ds_read_b128 v[190:193], v189 offset:33792
	ds_read_b128 v[194:197], v189 offset:34816
	ds_read_b128 v[198:201], v189 offset:35840
	ds_read_b128 v[202:205], v189 offset:36864
	ds_read_b128 v[206:209], v189 offset:37888
	ds_read_b128 v[210:213], v189 offset:38912
	ds_read_b128 v[214:217], v189 offset:39936
	global_load_lds_dwordx4 v[228:229], off
	v_lshl_add_u64 v[228:229], s[28:29], 0, v[134:135]
	s_mov_b32 m0, s45
	s_nop 0
	global_load_lds_dwordx4 v[228:229], off
	s_waitcnt vmcnt(8)
	s_waitcnt lgkmcnt(0)
	s_barrier
	s_setprio 1
	s_waitcnt lgkmcnt(0)
	v_mfma_i32_16x16x64_i8 v[126:129], v[148:151], v[180:183], v[126:129]
	v_mfma_i32_16x16x64_i8 v[122:125], v[156:159], v[180:183], v[122:125]
	v_mfma_i32_16x16x64_i8 v[118:121], v[148:151], v[194:197], v[118:121]
	v_mfma_i32_16x16x64_i8 v[114:117], v[156:159], v[194:197], v[114:117]
	v_mfma_i32_16x16x64_i8 v[106:109], v[148:151], v[202:205], v[106:109]
	v_mfma_i32_16x16x64_i8 v[98:101], v[156:159], v[202:205], v[98:101]
	v_mfma_i32_16x16x64_i8 v[90:93], v[148:151], v[210:213], v[90:93]
	v_mfma_i32_16x16x64_i8 v[82:85], v[156:159], v[210:213], v[82:85]
	v_mfma_i32_16x16x64_i8 v[126:129], v[152:155], v[190:193], v[126:129]
	v_mfma_i32_16x16x64_i8 v[122:125], v[160:163], v[190:193], v[122:125]
	v_mfma_i32_16x16x64_i8 v[118:121], v[152:155], v[198:201], v[118:121]
	v_mfma_i32_16x16x64_i8 v[114:117], v[160:163], v[198:201], v[114:117]
	v_mfma_i32_16x16x64_i8 v[106:109], v[152:155], v[206:209], v[106:109]
	v_mfma_i32_16x16x64_i8 v[98:101], v[160:163], v[206:209], v[98:101]
	v_mfma_i32_16x16x64_i8 v[90:93], v[152:155], v[214:217], v[90:93]
	v_mfma_i32_16x16x64_i8 v[82:85], v[160:163], v[214:217], v[82:85]
	s_setprio 0
	s_setprio 1
	v_mfma_i32_16x16x64_i8 v[110:113], v[164:167], v[180:183], v[110:113]
	v_mfma_i32_16x16x64_i8 v[102:105], v[172:175], v[180:183], v[102:105]
	v_mfma_i32_16x16x64_i8 v[94:97], v[164:167], v[194:197], v[94:97]
	v_mfma_i32_16x16x64_i8 v[86:89], v[172:175], v[194:197], v[86:89]
	v_mfma_i32_16x16x64_i8 v[78:81], v[164:167], v[202:205], v[78:81]
	v_mfma_i32_16x16x64_i8 v[74:77], v[172:175], v[202:205], v[74:77]
	v_mfma_i32_16x16x64_i8 v[70:73], v[164:167], v[210:213], v[70:73]
	v_mfma_i32_16x16x64_i8 v[66:69], v[172:175], v[210:213], v[66:69]
	v_mfma_i32_16x16x64_i8 v[110:113], v[168:171], v[190:193], v[110:113]
	v_mfma_i32_16x16x64_i8 v[102:105], v[176:179], v[190:193], v[102:105]
	v_mfma_i32_16x16x64_i8 v[94:97], v[168:171], v[198:201], v[94:97]
	v_mfma_i32_16x16x64_i8 v[86:89], v[176:179], v[198:201], v[86:89]
	v_mfma_i32_16x16x64_i8 v[78:81], v[168:171], v[206:209], v[78:81]
	v_mfma_i32_16x16x64_i8 v[74:77], v[176:179], v[206:209], v[74:77]
	v_mfma_i32_16x16x64_i8 v[70:73], v[168:171], v[214:217], v[70:73]
	v_mfma_i32_16x16x64_i8 v[66:69], v[176:179], v[214:217], v[66:69]
	s_setprio 0
	s_barrier
	s_add_i32 s28, s61, s41
	v_lshl_add_u64 v[184:185], v[184:185], 0, s[18:19]
	s_mov_b32 m0, s28
	ds_read_b128 v[180:183], v189 offset:49152
	ds_read_b128 v[190:193], v189 offset:50176
	ds_read_b128 v[194:197], v189 offset:51200
	ds_read_b128 v[198:201], v189 offset:52224
	ds_read_b128 v[202:205], v189 offset:53248
	ds_read_b128 v[206:209], v189 offset:54272
	ds_read_b128 v[210:213], v189 offset:55296
	ds_read_b128 v[214:217], v189 offset:56320
	global_load_lds_dwordx4 v[184:185], off
	v_lshl_add_u64 v[184:185], v[218:219], 0, s[18:19]
	s_add_i32 m0, s28, 0x2000
	s_add_i32 s28, s62, s41
	global_load_lds_dwordx4 v[184:185], off
	v_lshl_add_u64 v[184:185], v[220:221], 0, s[18:19]
	s_mov_b32 m0, s28
	s_nop 0
	global_load_lds_dwordx4 v[184:185], off
	v_lshl_add_u64 v[184:185], v[222:223], 0, s[18:19]
	s_add_i32 m0, s28, 0x2000
	s_nop 0
	global_load_lds_dwordx4 v[184:185], off
	s_waitcnt vmcnt(6)
	s_waitcnt lgkmcnt(0)
	s_barrier
	s_setprio 1
	s_waitcnt lgkmcnt(0)
	v_mfma_i32_16x16x64_i8 v[62:65], v[148:151], v[180:183], v[62:65]
	v_mfma_i32_16x16x64_i8 v[58:61], v[156:159], v[180:183], v[58:61]
	v_mfma_i32_16x16x64_i8 v[54:57], v[148:151], v[194:197], v[54:57]
	v_mfma_i32_16x16x64_i8 v[50:53], v[156:159], v[194:197], v[50:53]
	v_lshl_add_u64 v[184:185], v[224:225], 0, s[18:19]
	s_mov_b32 m0, s49
	s_nop 0
	global_load_lds_dwordx4 v[184:185], off
	v_mfma_i32_16x16x64_i8 v[42:45], v[148:151], v[202:205], v[42:45]
	v_mfma_i32_16x16x64_i8 v[34:37], v[156:159], v[202:205], v[34:37]
	v_mfma_i32_16x16x64_i8 v[26:29], v[148:151], v[210:213], v[26:29]
	v_mfma_i32_16x16x64_i8 v[18:21], v[156:159], v[210:213], v[18:21]
	v_mfma_i32_16x16x64_i8 v[62:65], v[152:155], v[190:193], v[62:65]
	v_mfma_i32_16x16x64_i8 v[58:61], v[160:163], v[190:193], v[58:61]
	v_mfma_i32_16x16x64_i8 v[54:57], v[152:155], v[198:201], v[54:57]
	v_mfma_i32_16x16x64_i8 v[50:53], v[160:163], v[198:201], v[50:53]
	v_mfma_i32_16x16x64_i8 v[42:45], v[152:155], v[206:209], v[42:45]
	v_mfma_i32_16x16x64_i8 v[34:37], v[160:163], v[206:209], v[34:37]
	v_mfma_i32_16x16x64_i8 v[26:29], v[152:155], v[214:217], v[26:29]
	v_mfma_i32_16x16x64_i8 v[18:21], v[160:163], v[214:217], v[18:21]
	s_setprio 0
	s_setprio 1
	v_mfma_i32_16x16x64_i8 v[46:49], v[164:167], v[180:183], v[46:49]
	v_mfma_i32_16x16x64_i8 v[38:41], v[172:175], v[180:183], v[38:41]
	v_mfma_i32_16x16x64_i8 v[30:33], v[164:167], v[194:197], v[30:33]
	v_mfma_i32_16x16x64_i8 v[22:25], v[172:175], v[194:197], v[22:25]
	v_lshl_add_u64 v[184:185], v[226:227], 0, s[18:19]
	s_mov_b32 m0, s50
	s_nop 0
	global_load_lds_dwordx4 v[184:185], off
	v_mfma_i32_16x16x64_i8 v[14:17], v[164:167], v[202:205], v[14:17]
	v_mfma_i32_16x16x64_i8 v[10:13], v[172:175], v[202:205], v[10:13]
	v_mfma_i32_16x16x64_i8 v[6:9], v[164:167], v[210:213], v[6:9]
	v_mfma_i32_16x16x64_i8 v[2:5], v[172:175], v[210:213], v[2:5]
	v_mfma_i32_16x16x64_i8 v[46:49], v[168:171], v[190:193], v[46:49]
	v_mfma_i32_16x16x64_i8 v[38:41], v[176:179], v[190:193], v[38:41]
	v_mfma_i32_16x16x64_i8 v[30:33], v[168:171], v[198:201], v[30:33]
	v_mfma_i32_16x16x64_i8 v[22:25], v[176:179], v[198:201], v[22:25]
	v_mfma_i32_16x16x64_i8 v[14:17], v[168:171], v[206:209], v[14:17]
	v_mfma_i32_16x16x64_i8 v[10:13], v[176:179], v[206:209], v[10:13]
	v_mfma_i32_16x16x64_i8 v[6:9], v[168:171], v[214:217], v[6:9]
	v_mfma_i32_16x16x64_i8 v[2:5], v[176:179], v[214:217], v[2:5]
	s_setprio 0
	s_barrier
	s_add_u32 s26, s26, 0x100
	s_addc_u32 s27, s27, 0
	s_add_u32 s34, s34, 0x100
	s_addc_u32 s35, s35, 0
	s_cmp_ge_i32 s60, s51
	s_mov_b32 s28, s60
	s_cbranch_scc0 .LBB0_3798
	v_cvt_f32_i32_e32 v172, v126
	v_cvt_f32_i32_e32 v173, v127
	v_cvt_f32_i32_e32 v170, v128
	v_cvt_f32_i32_e32 v171, v129
	v_cvt_f32_i32_e32 v174, v122
	v_cvt_f32_i32_e32 v175, v123
	v_cvt_f32_i32_e32 v176, v124
	v_cvt_f32_i32_e32 v177, v125
	v_cvt_f32_i32_e32 v180, v110
	v_cvt_f32_i32_e32 v181, v111
	v_cvt_f32_i32_e32 v182, v112
	v_cvt_f32_i32_e32 v183, v113
	v_cvt_f32_i32_e32 v178, v102
	v_cvt_f32_i32_e32 v179, v103
	v_cvt_f32_i32_e32 v184, v104
	v_cvt_f32_i32_e32 v185, v105
	v_cvt_f32_i32_e32 v152, v118
	v_cvt_f32_i32_e32 v153, v119
	v_cvt_f32_i32_e32 v154, v120
	v_cvt_f32_i32_e32 v155, v121
	v_cvt_f32_i32_e32 v156, v114
	v_cvt_f32_i32_e32 v157, v115
	v_cvt_f32_i32_e32 v158, v116
	v_cvt_f32_i32_e32 v159, v117
	v_cvt_f32_i32_e32 v160, v94
	v_cvt_f32_i32_e32 v161, v95
	v_cvt_f32_i32_e32 v162, v96
	v_cvt_f32_i32_e32 v163, v97
	v_cvt_f32_i32_e32 v164, v86
	v_cvt_f32_i32_e32 v165, v87
	v_cvt_f32_i32_e32 v166, v88
	v_cvt_f32_i32_e32 v167, v89
	v_cvt_f32_i32_e32 v118, v106
	v_cvt_f32_i32_e32 v119, v107
	v_cvt_f32_i32_e32 v120, v108
	v_cvt_f32_i32_e32 v121, v109
	v_cvt_f32_i32_e32 v122, v98
	v_cvt_f32_i32_e32 v123, v99
	v_cvt_f32_i32_e32 v124, v100
	v_cvt_f32_i32_e32 v125, v101
	v_cvt_f32_i32_e32 v126, v78
	v_cvt_f32_i32_e32 v127, v79
	v_cvt_f32_i32_e32 v128, v80
	v_cvt_f32_i32_e32 v129, v81
	v_cvt_f32_i32_e32 v148, v74
	v_cvt_f32_i32_e32 v149, v75
	v_cvt_f32_i32_e32 v150, v76
	v_cvt_f32_i32_e32 v151, v77
	v_cvt_f32_i32_e32 v102, v90
	v_cvt_f32_i32_e32 v103, v91
	v_cvt_f32_i32_e32 v104, v92
	v_cvt_f32_i32_e32 v105, v93
	v_cvt_f32_i32_e32 v106, v82
	v_cvt_f32_i32_e32 v107, v83
	v_cvt_f32_i32_e32 v108, v84
	v_cvt_f32_i32_e32 v109, v85
	v_cvt_f32_i32_e32 v110, v70
	v_cvt_f32_i32_e32 v111, v71
	v_cvt_f32_i32_e32 v112, v72
	v_cvt_f32_i32_e32 v113, v73
	v_cvt_f32_i32_e32 v114, v66
	v_cvt_f32_i32_e32 v115, v67
	v_cvt_f32_i32_e32 v116, v68
	v_cvt_f32_i32_e32 v117, v69
	v_cvt_f32_i32_e32 v82, v62
	v_cvt_f32_i32_e32 v83, v63
	v_cvt_f32_i32_e32 v84, v64
	v_cvt_f32_i32_e32 v85, v65
	v_cvt_f32_i32_e32 v86, v58
	v_cvt_f32_i32_e32 v87, v59
	v_cvt_f32_i32_e32 v88, v60
	v_cvt_f32_i32_e32 v89, v61
	v_cvt_f32_i32_e32 v92, v46
	v_cvt_f32_i32_e32 v93, v47
	v_cvt_f32_i32_e32 v94, v48
	v_cvt_f32_i32_e32 v95, v49
	v_cvt_f32_i32_e32 v96, v38
	v_cvt_f32_i32_e32 v97, v39
	v_cvt_f32_i32_e32 v98, v40
	v_cvt_f32_i32_e32 v99, v41
	v_cvt_f32_i32_e32 v66, v54
	v_cvt_f32_i32_e32 v67, v55
	v_cvt_f32_i32_e32 v68, v56
	v_cvt_f32_i32_e32 v69, v57
	v_cvt_f32_i32_e32 v70, v50
	v_cvt_f32_i32_e32 v71, v51
	v_cvt_f32_i32_e32 v72, v52
	v_cvt_f32_i32_e32 v73, v53
	v_cvt_f32_i32_e32 v74, v30
	v_cvt_f32_i32_e32 v75, v31
	v_cvt_f32_i32_e32 v76, v32
	v_cvt_f32_i32_e32 v77, v33
	v_cvt_f32_i32_e32 v78, v22
	v_cvt_f32_i32_e32 v79, v23
	v_cvt_f32_i32_e32 v80, v24
	v_cvt_f32_i32_e32 v81, v25
	v_cvt_f32_i32_e32 v50, v42
	v_cvt_f32_i32_e32 v51, v43
	v_cvt_f32_i32_e32 v52, v44
	v_cvt_f32_i32_e32 v53, v45
	v_cvt_f32_i32_e32 v54, v34
	v_cvt_f32_i32_e32 v55, v35
	v_cvt_f32_i32_e32 v56, v36
	v_cvt_f32_i32_e32 v57, v37
	v_cvt_f32_i32_e32 v58, v14
	v_cvt_f32_i32_e32 v59, v15
	v_cvt_f32_i32_e32 v60, v16
	v_cvt_f32_i32_e32 v61, v17
	v_cvt_f32_i32_e32 v62, v10
	v_cvt_f32_i32_e32 v63, v11
	v_cvt_f32_i32_e32 v64, v12
	v_cvt_f32_i32_e32 v65, v13
	v_cvt_f32_i32_e32 v34, v26
	v_cvt_f32_i32_e32 v35, v27
	v_cvt_f32_i32_e32 v36, v28
	v_cvt_f32_i32_e32 v37, v29
	v_cvt_f32_i32_e32 v38, v18
	v_cvt_f32_i32_e32 v39, v19
	v_cvt_f32_i32_e32 v40, v20
	v_cvt_f32_i32_e32 v41, v21
	v_cvt_f32_i32_e32 v42, v6
	v_cvt_f32_i32_e32 v43, v7
	v_cvt_f32_i32_e32 v44, v8
	v_cvt_f32_i32_e32 v45, v9
	v_cvt_f32_i32_e32 v46, v2
	v_cvt_f32_i32_e32 v47, v3
	v_cvt_f32_i32_e32 v48, v4
	v_cvt_f32_i32_e32 v49, v5
